# attention score masking simplified (one per-tile threshold instead of per-element select chains) and layer-1 FFN1/W_in conversion moved into the mixer phase work queue
# baseline (speedup 1.0000x reference)
; __device__ __forceinline__ int opaque_tid() { int t = threadIdx.x; asm volatile("" : "+v"(t)); return t; }
; #define CVT_LOAD(tile_) do { const int k0_ = ((tile_) / ntn) << 7, n0_ = ((tile_) % ntn) << 6; \
;         _Pragma("unroll") for (int pp = 0; pp < 4; ++pp) pv[pp] = *(const float4*)(src + (size_t)(k0_ + lk + 32 * pp) * N + n0_ + ln4); } while (0)
; __device__ __forceinline__ void convT_job(const float* __restrict__ src, bf16_t* __restrict__ dst, int K, int N, int mode, float* t) {
;     const int tid = opaque_tid(), ntn = N >> 6, ntiles = (K >> 7) * ntn;
;     const int lk = tid >> 4, ln4 = (tid & 15) * 4;
;     float4 pv[4];
;     ...
;     int tile = blockIdx.x;
;     if (tile < ntiles) CVT_LOAD(tile);
; __device__ __forceinline__ void run_phase(const Params& p, int ph, unsigned char* smem, int rep) {
;     ...
;     } else if (k == 5) {
;         unsigned* ctr = (unsigned*)(p.ws + OFF_CTL) + l * 64 + rep * 128;
;         int* s_item = (int*)(smem + LDS_BYTES - 16);
;         for (;;) {
;             __syncthreads();
;             if (threadIdx.x == 0) *s_item = (int)atomicAdd(ctr, 1u);
;             __syncthreads();
;             const int it = *s_item;
;             if (it >= 784) break;
;     ...
;             if (rep == 1 && !((PROBE_SUB == 1 && it < 16) || (PROBE_SUB == 2 && it >= 16 && it < 528) || (PROBE_SUB == 3 && it >= 528) || (PROBE_SUB == 4 && it >= 16))) continue;
;     ...
;             if (it < 16) hgrn_item(p, l, it, smem, rep);
;             else if (it < 528) attn_item(p, it - 16, smem);
;             else rgpost_item(p, it - 528, smem);
;         }
.Lq5_conv:
	s_sub_u32 s40, s50, 0x310
	s_mul_hi_u32 s0, s40, 0x2e8ba2f
	s_mul_i32 s1, s0, 88
	s_sub_u32 s40, s40, s1
	s_lshl_b32 s40, s40, 4
	s_add_u32 s53, s40, 16
	s_mov_b32 s52, s0
	v_lshrrev_b32_e32 v6, 6, v234
	v_and_b32_e32 v25, 63, v234
	v_lshrrev_b32_e32 v26, 3, v234
	v_readfirstlane_b32 s46, v6
	v_and_b32_e32 v27, 7, v234
	v_readlane_b32 s54, v255, 28
	v_readlane_b32 s55, v255, 29
	s_lshl_b32 s46, s46, 12
	v_lshrrev_b32_e32 v28, 2, v26
	v_xor_b32_e32 v28, v28, v27
	v_lshlrev_b32_e32 v28, 4, v28
	v_and_b32_e32 v29, 3, v26
	v_lshl_or_b32 v28, v29, 2, v28
	v_lshl_or_b32 v4, v27, 12, v28
	v_lshrrev_b32_e32 v30, 4, v25
	v_lshl_add_u32 v30, v6, 4, v30
	v_and_b32_e32 v31, 15, v25
	v_xor_b32_e32 v31, v31, v6
	v_lshlrev_b32_e32 v31, 4, v31
	v_lshlrev_b32_e32 v27, 5, v27
	s_cmp_eq_u32 s52, 0
	s_cbranch_scc0 .Lq5_n0
	v_mov_b32_e32 v29, 0x5800
	v_mov_b32_e32 v28, 0x1000
	v_mad_u32_u24 v0, v30, v29, v31
	v_mad_u32_u24 v5, v26, v28, v27
	v_add_u32_e32 v1, 0x16000, v0
	v_add_u32_e32 v2, 0x2c000, v0
	v_add_u32_e32 v3, 0x42000, v0
	s_barrier
	s_mov_b32 s41, 0
	s_mov_b32 s47, s40
	s_mov_b32 s48, s46
	s_mul_hi_u32 s0, s47, 0x2e8ba3
	s_mul_i32 s1, s0, 1408
	s_sub_u32 s1, s47, s1
	s_mul_hi_u32 s2, s1, 0x2e8ba2f
	s_mul_i32 s8, s2, 88
	s_sub_u32 s8, s1, s8
	s_mul_i32 s9, s0, 0x2c00000
	s_mul_i32 s28, s2, 0x2c0000
	s_add_u32 s9, s9, s28
	s_lshl_b32 s8, s8, 8
	s_add_u32 s9, s9, s8
	s_add_u32 s9, s9, 0x5800000
	s_add_u32 s42, s70, s9
	s_addc_u32 s43, s71, 0
	s_mov_b32 m0, s48
	s_add_u32 s49, s48, 0x400
	global_load_lds_dwordx4 v0, s[42:43] nt
	s_mov_b32 m0, s49
	s_add_u32 s49, s48, 0x800
	global_load_lds_dwordx4 v1, s[42:43] nt
	s_mov_b32 m0, s49
	s_add_u32 s49, s48, 0xc00
	global_load_lds_dwordx4 v2, s[42:43] nt
	s_mov_b32 m0, s49
	s_nop 0
	global_load_lds_dwordx4 v3, s[42:43] nt
	global_load_dword v24, v173, s[70:71]
	global_load_dword v24, v173, s[70:71]
	s_add_u32 s47, s40, 1
	s_add_u32 s48, s46, 0x8000
	s_cmp_lt_u32 s47, s53
	s_cbranch_scc0 .Lq5_qgate_pd1
	s_mul_hi_u32 s0, s47, 0x2e8ba3
	s_mul_i32 s1, s0, 1408
	s_sub_u32 s1, s47, s1
	s_mul_hi_u32 s2, s1, 0x2e8ba2f
	s_mul_i32 s8, s2, 88
	s_sub_u32 s8, s1, s8
	s_mul_i32 s9, s0, 0x2c00000
	s_mul_i32 s28, s2, 0x2c0000
	s_add_u32 s9, s9, s28
	s_lshl_b32 s8, s8, 8
	s_add_u32 s9, s9, s8
	s_add_u32 s9, s9, 0x5800000
	s_add_u32 s42, s70, s9
	s_addc_u32 s43, s71, 0
	s_mov_b32 m0, s48
	s_add_u32 s49, s48, 0x400
	global_load_lds_dwordx4 v0, s[42:43] nt
	s_mov_b32 m0, s49
	s_add_u32 s49, s48, 0x800
	global_load_lds_dwordx4 v1, s[42:43] nt
	s_mov_b32 m0, s49
	s_add_u32 s49, s48, 0xc00
	global_load_lds_dwordx4 v2, s[42:43] nt
	s_mov_b32 m0, s49
	s_nop 0
	global_load_lds_dwordx4 v3, s[42:43] nt
	s_branch .Lq5_qgate_pj1

; #define CVT_LOAD(tile_) do { const int k0_ = ((tile_) / ntn) << 7, n0_ = ((tile_) % ntn) << 6; \
;         _Pragma("unroll") for (int pp = 0; pp < 4; ++pp) pv[pp] = *(const float4*)(src + (size_t)(k0_ + lk + 32 * pp) * N + n0_ + ln4); } while (0)
; __device__ __forceinline__ void convT_job(const float* __restrict__ src, bf16_t* __restrict__ dst, int K, int N, int mode, float* t) {
;     ...
;         if (tile + (int)gridDim.x < ntiles) CVT_LOAD(tile + (int)gridDim.x);
.Lq5_qgate_pj1:
	global_load_dword v24, v173, s[70:71]
	global_load_dword v24, v173, s[70:71]
	s_add_u32 s47, s40, 2
	s_add_u32 s48, s46, 0x10000
	s_cmp_lt_u32 s47, s53
	s_cbranch_scc0 .Lq5_qgate_pd2
	s_mul_hi_u32 s0, s47, 0x2e8ba3
	s_mul_i32 s1, s0, 1408
	s_sub_u32 s1, s47, s1
	s_mul_hi_u32 s2, s1, 0x2e8ba2f
	s_mul_i32 s8, s2, 88
	s_sub_u32 s8, s1, s8
	s_mul_i32 s9, s0, 0x2c00000
	s_mul_i32 s28, s2, 0x2c0000
	s_add_u32 s9, s9, s28
	s_lshl_b32 s8, s8, 8
	s_add_u32 s9, s9, s8
	s_add_u32 s9, s9, 0x5800000
	s_add_u32 s42, s70, s9
	s_addc_u32 s43, s71, 0
	s_mov_b32 m0, s48
	s_add_u32 s49, s48, 0x400
	global_load_lds_dwordx4 v0, s[42:43] nt
	s_mov_b32 m0, s49
	s_add_u32 s49, s48, 0x800
	global_load_lds_dwordx4 v1, s[42:43] nt
	s_mov_b32 m0, s49
	s_add_u32 s49, s48, 0xc00
	global_load_lds_dwordx4 v2, s[42:43] nt
	s_mov_b32 m0, s49
	s_nop 0
	global_load_lds_dwordx4 v3, s[42:43] nt
	s_branch .Lq5_qgate_pj2

; #define CVT_LOAD(tile_) do { const int k0_ = ((tile_) / ntn) << 7, n0_ = ((tile_) % ntn) << 6; \
;         _Pragma("unroll") for (int pp = 0; pp < 4; ++pp) pv[pp] = *(const float4*)(src + (size_t)(k0_ + lk + 32 * pp) * N + n0_ + ln4); } while (0)
; __device__ __forceinline__ void convT_job(const float* __restrict__ src, bf16_t* __restrict__ dst, int K, int N, int mode, float* t) {
;     ...
; #pragma unroll 1
;     for (; tile < ntiles; tile += gridDim.x) {
;         const int k0 = (tile / ntn) << 7, n0 = (tile % ntn) << 6;
; #pragma unroll
;         for (int pp = 0; pp < 4; ++pp) { const int k = lk + 32 * pp; t[k * 65 + ln4] = pv[pp].x; t[k * 65 + ln4 + 1] = pv[pp].y; t[k * 65 + ln4 + 2] = pv[pp].z; t[k * 65 + ln4 + 3] = pv[pp].w; }
;         if (tile + (int)gridDim.x < ntiles) CVT_LOAD(tile + (int)gridDim.x);
.Lq5_qgate_loop:
	s_waitcnt vmcnt(14)
	s_barrier
	s_add_u32 s47, s40, 3
	s_add_u32 s48, s41, 0x18000
	s_and_b32 s48, s48, 0x1ffff
	s_add_u32 s48, s48, s46
	s_cmp_lt_u32 s47, s53
	s_cbranch_scc0 .Lq5_qgate_ld
	s_mul_hi_u32 s0, s47, 0x2e8ba3
	s_mul_i32 s1, s0, 1408
	s_sub_u32 s1, s47, s1
	s_mul_hi_u32 s2, s1, 0x2e8ba2f
	s_mul_i32 s8, s2, 88
	s_sub_u32 s8, s1, s8
	s_mul_i32 s9, s0, 0x2c00000
	s_mul_i32 s28, s2, 0x2c0000
	s_add_u32 s9, s9, s28
	s_lshl_b32 s8, s8, 8
	s_add_u32 s9, s9, s8
	s_add_u32 s9, s9, 0x5800000
	s_add_u32 s42, s70, s9
	s_addc_u32 s43, s71, 0
	s_mov_b32 m0, s48
	s_add_u32 s49, s48, 0x400
	global_load_lds_dwordx4 v0, s[42:43] nt
	s_mov_b32 m0, s49
	s_add_u32 s49, s48, 0x800
	global_load_lds_dwordx4 v1, s[42:43] nt
	s_mov_b32 m0, s49
	s_add_u32 s49, s48, 0xc00
	global_load_lds_dwordx4 v2, s[42:43] nt
	s_mov_b32 m0, s49
	s_nop 0
	global_load_lds_dwordx4 v3, s[42:43] nt
	s_branch .Lq5_qgate_lj

; __device__ __forceinline__ unsigned cvt_pk_bf16(float lo, float hi) { unsigned r; asm volatile("v_cvt_pk_bf16_f32 %0, %1, %2" : "=v"(r) : "v"(lo), "v"(hi)); return r; }
; __device__ __forceinline__ void lds_barrier() { asm volatile("s_waitcnt lgkmcnt(0)" ::: "memory"); __builtin_amdgcn_s_barrier(); asm volatile("" ::: "memory"); }
; __device__ __forceinline__ void convT_job(const float* __restrict__ src, bf16_t* __restrict__ dst, int K, int N, int mode, float* t) {
;     ...
;         lds_barrier();
;         const int n = tid >> 3, k16 = (tid & 7) * 16;
;         float v[16];
; #pragma unroll
;         for (int j = 0; j < 16; ++j) v[j] = t[(k16 + j) * 65 + n];
;         const int nn = n0 + n;
;         const int row = mode == 0 ? nn : (256 * (nn >> 7) + (nn & 127) + (mode == 2 ? 128 : 0));
;         u32x4 w0, w1; w0.x = cvt_pk_bf16(v[0], v[1]); w0.y = cvt_pk_bf16(v[2], v[3]); w0.z = cvt_pk_bf16(v[4], v[5]); w0.w = cvt_pk_bf16(v[6], v[7]);
;         w1.x = cvt_pk_bf16(v[8], v[9]); w1.y = cvt_pk_bf16(v[10], v[11]); w1.z = cvt_pk_bf16(v[12], v[13]); w1.w = cvt_pk_bf16(v[14], v[15]);
;         bf16_t* d = dst + (size_t)row * K + k0 + k16;
;         *(u32x4*)d = w0; *(u32x4*)(d + 8) = w1;
;         lds_barrier();
.Lq5_qgate_lj:
	v_add_u32_e32 v7, s41, v4
	ds_read2st64_b32 v[8:9], v7 offset0:0 offset1:1
	ds_read2st64_b32 v[10:11], v7 offset0:2 offset1:3
	ds_read2st64_b32 v[12:13], v7 offset0:4 offset1:5
	ds_read2st64_b32 v[14:15], v7 offset0:6 offset1:7
	ds_read2st64_b32 v[16:17], v7 offset0:8 offset1:9
	ds_read2st64_b32 v[18:19], v7 offset0:10 offset1:11
	ds_read2st64_b32 v[20:21], v7 offset0:12 offset1:13
	ds_read2st64_b32 v[22:23], v7 offset0:14 offset1:15
	s_mul_hi_u32 s0, s40, 0x2e8ba3
	s_mul_i32 s1, s0, 1408
	s_sub_u32 s1, s40, s1
	s_mul_hi_u32 s2, s1, 0x2e8ba2f
	s_mul_i32 s8, s2, 88
	s_sub_u32 s8, s1, s8
	s_lshr_b32 s9, s8, 1
	s_lshl_b32 s9, s9, 8
	s_and_b32 s28, s8, 1
	s_lshl_b32 s28, s28, 6
	s_add_u32 s9, s9, s28
	s_mul_i32 s9, s9, 0x1000
	s_mul_i32 s28, s0, 0x2c00000
	s_add_u32 s9, s9, s28
	s_lshl_b32 s2, s2, 8
	s_add_u32 s9, s9, s2
	s_add_u32 s9, s9, 0x5808000
	s_add_u32 s44, s54, s9
	s_addc_u32 s45, s55, 0
	s_waitcnt lgkmcnt(6)
	v_cvt_pk_bf16_f32 v8, v8, v9
	v_cvt_pk_bf16_f32 v9, v10, v11
	s_waitcnt lgkmcnt(4)
	v_cvt_pk_bf16_f32 v10, v12, v13
	v_cvt_pk_bf16_f32 v11, v14, v15
	s_waitcnt lgkmcnt(2)
	v_cvt_pk_bf16_f32 v12, v16, v17
	v_cvt_pk_bf16_f32 v13, v18, v19
	s_waitcnt lgkmcnt(0)
	v_cvt_pk_bf16_f32 v14, v20, v21
	v_cvt_pk_bf16_f32 v15, v22, v23
	global_store_dwordx4 v5, v[8:11], s[44:45]
	global_store_dwordx4 v5, v[12:15], s[44:45] offset:16
	s_add_u32 s40, s40, 1
	s_add_u32 s41, s41, 0x8000
	s_and_b32 s41, s41, 0x1ffff
	s_cmp_lt_u32 s40, s53
	s_cbranch_scc1 .Lq5_qgate_loop

; __device__ __forceinline__ int opaque_tid() { int t = threadIdx.x; asm volatile("" : "+v"(t)); return t; }
; #define CVT_LOAD(tile_) do { const int k0_ = ((tile_) / ntn) << 7, n0_ = ((tile_) % ntn) << 6; \
;         _Pragma("unroll") for (int pp = 0; pp < 4; ++pp) pv[pp] = *(const float4*)(src + (size_t)(k0_ + lk + 32 * pp) * N + n0_ + ln4); } while (0)
; __device__ __forceinline__ void convT_job(const float* __restrict__ src, bf16_t* __restrict__ dst, int K, int N, int mode, float* t) {
;     const int tid = opaque_tid(), ntn = N >> 6, ntiles = (K >> 7) * ntn;
;     const int lk = tid >> 4, ln4 = (tid & 15) * 4;
;     float4 pv[4];
;     ...
;     int tile = blockIdx.x;
;     if (tile < ntiles) CVT_LOAD(tile);
; __device__ __forceinline__ void phase_convert(const Params& p, unsigned char* smem) {
;     ...
;             convT_job(p.in[4] + wo, gu, 2048, 5632, 2, t);
.Lq5_n0:
	s_cmp_eq_u32 s52, 1
	s_cbranch_scc0 .Lq5_n1
	v_mov_b32_e32 v29, 0x5800
	v_mov_b32_e32 v28, 0x1000
	v_mad_u32_u24 v0, v30, v29, v31
	v_mad_u32_u24 v5, v26, v28, v27
	v_add_u32_e32 v1, 0x16000, v0
	v_add_u32_e32 v2, 0x2c000, v0
	v_add_u32_e32 v3, 0x42000, v0
	s_barrier
	s_mov_b32 s41, 0
	s_mov_b32 s47, s40
	s_mov_b32 s48, s46
	s_mul_hi_u32 s0, s47, 0x2e8ba3
	s_mul_i32 s1, s0, 1408
	s_sub_u32 s1, s47, s1
	s_mul_hi_u32 s2, s1, 0x2e8ba2f
	s_mul_i32 s8, s2, 88
	s_sub_u32 s8, s1, s8
	s_mul_i32 s9, s0, 0x2c00000
	s_mul_i32 s28, s2, 0x2c0000
	s_add_u32 s9, s9, s28
	s_lshl_b32 s8, s8, 8
	s_add_u32 s9, s9, s8
	s_add_u32 s9, s9, 0x5800000
	s_add_u32 s42, s72, s9
	s_addc_u32 s43, s73, 0
	s_mov_b32 m0, s48
	s_add_u32 s49, s48, 0x400
	global_load_lds_dwordx4 v0, s[42:43] nt
	s_mov_b32 m0, s49
	s_add_u32 s49, s48, 0x800
	global_load_lds_dwordx4 v1, s[42:43] nt
	s_mov_b32 m0, s49
	s_add_u32 s49, s48, 0xc00
	global_load_lds_dwordx4 v2, s[42:43] nt
	s_mov_b32 m0, s49
	s_nop 0
	global_load_lds_dwordx4 v3, s[42:43] nt
	global_load_dword v24, v173, s[72:73]
	global_load_dword v24, v173, s[72:73]
	s_add_u32 s47, s40, 1
	s_add_u32 s48, s46, 0x8000
	s_cmp_lt_u32 s47, s53
	s_cbranch_scc0 .Lq5_qup_pd1
	s_mul_hi_u32 s0, s47, 0x2e8ba3
	s_mul_i32 s1, s0, 1408
	s_sub_u32 s1, s47, s1
	s_mul_hi_u32 s2, s1, 0x2e8ba2f
	s_mul_i32 s8, s2, 88
	s_sub_u32 s8, s1, s8
	s_mul_i32 s9, s0, 0x2c00000
	s_mul_i32 s28, s2, 0x2c0000
	s_add_u32 s9, s9, s28
	s_lshl_b32 s8, s8, 8
	s_add_u32 s9, s9, s8
	s_add_u32 s9, s9, 0x5800000
	s_add_u32 s42, s72, s9
	s_addc_u32 s43, s73, 0
	s_mov_b32 m0, s48
	s_add_u32 s49, s48, 0x400
	global_load_lds_dwordx4 v0, s[42:43] nt
	s_mov_b32 m0, s49
	s_add_u32 s49, s48, 0x800
	global_load_lds_dwordx4 v1, s[42:43] nt
	s_mov_b32 m0, s49
	s_add_u32 s49, s48, 0xc00
	global_load_lds_dwordx4 v2, s[42:43] nt
	s_mov_b32 m0, s49
	s_nop 0
	global_load_lds_dwordx4 v3, s[42:43] nt
	s_branch .Lq5_qup_pj1

; #define CVT_LOAD(tile_) do { const int k0_ = ((tile_) / ntn) << 7, n0_ = ((tile_) % ntn) << 6; \
;         _Pragma("unroll") for (int pp = 0; pp < 4; ++pp) pv[pp] = *(const float4*)(src + (size_t)(k0_ + lk + 32 * pp) * N + n0_ + ln4); } while (0)
; __device__ __forceinline__ void convT_job(const float* __restrict__ src, bf16_t* __restrict__ dst, int K, int N, int mode, float* t) {
;     ...
;         if (tile + (int)gridDim.x < ntiles) CVT_LOAD(tile + (int)gridDim.x);
.Lq5_qup_pj1:
	global_load_dword v24, v173, s[72:73]
	global_load_dword v24, v173, s[72:73]
	s_add_u32 s47, s40, 2
	s_add_u32 s48, s46, 0x10000
	s_cmp_lt_u32 s47, s53
	s_cbranch_scc0 .Lq5_qup_pd2
	s_mul_hi_u32 s0, s47, 0x2e8ba3
	s_mul_i32 s1, s0, 1408
	s_sub_u32 s1, s47, s1
	s_mul_hi_u32 s2, s1, 0x2e8ba2f
	s_mul_i32 s8, s2, 88
	s_sub_u32 s8, s1, s8
	s_mul_i32 s9, s0, 0x2c00000
	s_mul_i32 s28, s2, 0x2c0000
	s_add_u32 s9, s9, s28
	s_lshl_b32 s8, s8, 8
	s_add_u32 s9, s9, s8
	s_add_u32 s9, s9, 0x5800000
	s_add_u32 s42, s72, s9
	s_addc_u32 s43, s73, 0
	s_mov_b32 m0, s48
	s_add_u32 s49, s48, 0x400
	global_load_lds_dwordx4 v0, s[42:43] nt
	s_mov_b32 m0, s49
	s_add_u32 s49, s48, 0x800
	global_load_lds_dwordx4 v1, s[42:43] nt
	s_mov_b32 m0, s49
	s_add_u32 s49, s48, 0xc00
	global_load_lds_dwordx4 v2, s[42:43] nt
	s_mov_b32 m0, s49
	s_nop 0
	global_load_lds_dwordx4 v3, s[42:43] nt
	s_branch .Lq5_qup_pj2

; #define CVT_LOAD(tile_) do { const int k0_ = ((tile_) / ntn) << 7, n0_ = ((tile_) % ntn) << 6; \
;         _Pragma("unroll") for (int pp = 0; pp < 4; ++pp) pv[pp] = *(const float4*)(src + (size_t)(k0_ + lk + 32 * pp) * N + n0_ + ln4); } while (0)
; __device__ __forceinline__ void convT_job(const float* __restrict__ src, bf16_t* __restrict__ dst, int K, int N, int mode, float* t) {
;     ...
; #pragma unroll 1
;     for (; tile < ntiles; tile += gridDim.x) {
;         const int k0 = (tile / ntn) << 7, n0 = (tile % ntn) << 6;
; #pragma unroll
;         for (int pp = 0; pp < 4; ++pp) { const int k = lk + 32 * pp; t[k * 65 + ln4] = pv[pp].x; t[k * 65 + ln4 + 1] = pv[pp].y; t[k * 65 + ln4 + 2] = pv[pp].z; t[k * 65 + ln4 + 3] = pv[pp].w; }
;         if (tile + (int)gridDim.x < ntiles) CVT_LOAD(tile + (int)gridDim.x);
.Lq5_qup_loop:
	s_waitcnt vmcnt(14)
	s_barrier
	s_add_u32 s47, s40, 3
	s_add_u32 s48, s41, 0x18000
	s_and_b32 s48, s48, 0x1ffff
	s_add_u32 s48, s48, s46
	s_cmp_lt_u32 s47, s53
	s_cbranch_scc0 .Lq5_qup_ld
	s_mul_hi_u32 s0, s47, 0x2e8ba3
	s_mul_i32 s1, s0, 1408
	s_sub_u32 s1, s47, s1
	s_mul_hi_u32 s2, s1, 0x2e8ba2f
	s_mul_i32 s8, s2, 88
	s_sub_u32 s8, s1, s8
	s_mul_i32 s9, s0, 0x2c00000
	s_mul_i32 s28, s2, 0x2c0000
	s_add_u32 s9, s9, s28
	s_lshl_b32 s8, s8, 8
	s_add_u32 s9, s9, s8
	s_add_u32 s9, s9, 0x5800000
	s_add_u32 s42, s72, s9
	s_addc_u32 s43, s73, 0
	s_mov_b32 m0, s48
	s_add_u32 s49, s48, 0x400
	global_load_lds_dwordx4 v0, s[42:43] nt
	s_mov_b32 m0, s49
	s_add_u32 s49, s48, 0x800
	global_load_lds_dwordx4 v1, s[42:43] nt
	s_mov_b32 m0, s49
	s_add_u32 s49, s48, 0xc00
	global_load_lds_dwordx4 v2, s[42:43] nt
	s_mov_b32 m0, s49
	s_nop 0
	global_load_lds_dwordx4 v3, s[42:43] nt
	s_branch .Lq5_qup_lj

; __device__ __forceinline__ unsigned cvt_pk_bf16(float lo, float hi) { unsigned r; asm volatile("v_cvt_pk_bf16_f32 %0, %1, %2" : "=v"(r) : "v"(lo), "v"(hi)); return r; }
; __device__ __forceinline__ void lds_barrier() { asm volatile("s_waitcnt lgkmcnt(0)" ::: "memory"); __builtin_amdgcn_s_barrier(); asm volatile("" ::: "memory"); }
; __device__ __forceinline__ void convT_job(const float* __restrict__ src, bf16_t* __restrict__ dst, int K, int N, int mode, float* t) {
;     ...
;         lds_barrier();
;         const int n = tid >> 3, k16 = (tid & 7) * 16;
;         float v[16];
; #pragma unroll
;         for (int j = 0; j < 16; ++j) v[j] = t[(k16 + j) * 65 + n];
;         const int nn = n0 + n;
;         const int row = mode == 0 ? nn : (256 * (nn >> 7) + (nn & 127) + (mode == 2 ? 128 : 0));
;         u32x4 w0, w1; w0.x = cvt_pk_bf16(v[0], v[1]); w0.y = cvt_pk_bf16(v[2], v[3]); w0.z = cvt_pk_bf16(v[4], v[5]); w0.w = cvt_pk_bf16(v[6], v[7]);
;         w1.x = cvt_pk_bf16(v[8], v[9]); w1.y = cvt_pk_bf16(v[10], v[11]); w1.z = cvt_pk_bf16(v[12], v[13]); w1.w = cvt_pk_bf16(v[14], v[15]);
;         bf16_t* d = dst + (size_t)row * K + k0 + k16;
;         *(u32x4*)d = w0; *(u32x4*)(d + 8) = w1;
;         lds_barrier();
.Lq5_qup_lj:
	v_add_u32_e32 v7, s41, v4
	ds_read2st64_b32 v[8:9], v7 offset0:0 offset1:1
	ds_read2st64_b32 v[10:11], v7 offset0:2 offset1:3
	ds_read2st64_b32 v[12:13], v7 offset0:4 offset1:5
	ds_read2st64_b32 v[14:15], v7 offset0:6 offset1:7
	ds_read2st64_b32 v[16:17], v7 offset0:8 offset1:9
	ds_read2st64_b32 v[18:19], v7 offset0:10 offset1:11
	ds_read2st64_b32 v[20:21], v7 offset0:12 offset1:13
	ds_read2st64_b32 v[22:23], v7 offset0:14 offset1:15
	s_mul_hi_u32 s0, s40, 0x2e8ba3
	s_mul_i32 s1, s0, 1408
	s_sub_u32 s1, s40, s1
	s_mul_hi_u32 s2, s1, 0x2e8ba2f
	s_mul_i32 s8, s2, 88
	s_sub_u32 s8, s1, s8
	s_lshr_b32 s9, s8, 1
	s_lshl_b32 s9, s9, 8
	s_and_b32 s28, s8, 1
	s_lshl_b32 s28, s28, 6
	s_add_u32 s9, s9, s28
	s_add_u32 s9, s9, 128
	s_mul_i32 s9, s9, 0x1000
	s_mul_i32 s28, s0, 0x2c00000
	s_add_u32 s9, s9, s28
	s_lshl_b32 s2, s2, 8
	s_add_u32 s9, s9, s2
	s_add_u32 s9, s9, 0x5808000
	s_add_u32 s44, s54, s9
	s_addc_u32 s45, s55, 0
	s_waitcnt lgkmcnt(6)
	v_cvt_pk_bf16_f32 v8, v8, v9
	v_cvt_pk_bf16_f32 v9, v10, v11
	s_waitcnt lgkmcnt(4)
	v_cvt_pk_bf16_f32 v10, v12, v13
	v_cvt_pk_bf16_f32 v11, v14, v15
	s_waitcnt lgkmcnt(2)
	v_cvt_pk_bf16_f32 v12, v16, v17
	v_cvt_pk_bf16_f32 v13, v18, v19
	s_waitcnt lgkmcnt(0)
	v_cvt_pk_bf16_f32 v14, v20, v21
	v_cvt_pk_bf16_f32 v15, v22, v23
	global_store_dwordx4 v5, v[8:11], s[44:45]
	global_store_dwordx4 v5, v[12:15], s[44:45] offset:16
	s_add_u32 s40, s40, 1
	s_add_u32 s41, s41, 0x8000
	s_and_b32 s41, s41, 0x1ffff
	s_cmp_lt_u32 s40, s53
	s_cbranch_scc1 .Lq5_qup_loop

; __device__ __forceinline__ int opaque_tid() { int t = threadIdx.x; asm volatile("" : "+v"(t)); return t; }
; #define CVT_LOAD(tile_) do { const int k0_ = ((tile_) / ntn) << 7, n0_ = ((tile_) % ntn) << 6; \
;         _Pragma("unroll") for (int pp = 0; pp < 4; ++pp) pv[pp] = *(const float4*)(src + (size_t)(k0_ + lk + 32 * pp) * N + n0_ + ln4); } while (0)
; __device__ __forceinline__ void convT_job(const float* __restrict__ src, bf16_t* __restrict__ dst, int K, int N, int mode, float* t) {
;     const int tid = opaque_tid(), ntn = N >> 6, ntiles = (K >> 7) * ntn;
;     const int lk = tid >> 4, ln4 = (tid & 15) * 4;
;     float4 pv[4];
;     ...
;     int tile = blockIdx.x;
;     if (tile < ntiles) CVT_LOAD(tile);
; __device__ __forceinline__ void phase_convert(const Params& p, unsigned char* smem) {
;     ...
;             convT_job(p.in[5] + wo, (bf16_t*)(p.ws + OFF_DN + (size_t)(l * 2 + f) * SZ_DN), 5632, 2048, 0, t);
.Lq5_n1:
	s_cmp_eq_u32 s52, 2
	s_cbranch_scc0 .Lq5_n2
	v_mov_b32_e32 v29, 0x2000
	v_mov_b32_e32 v28, 0x2c00
	v_mad_u32_u24 v0, v30, v29, v31
	v_mad_u32_u24 v5, v26, v28, v27
	v_add_u32_e32 v1, 0x8000, v0
	v_add_u32_e32 v2, 0x10000, v0
	v_add_u32_e32 v3, 0x18000, v0
	s_barrier
	s_mov_b32 s41, 0
	s_mov_b32 s47, s40
	s_mov_b32 s48, s46
	s_mul_hi_u32 s0, s47, 0x2e8ba3
	s_mul_i32 s1, s0, 1408
	s_sub_u32 s1, s47, s1
	s_mul_hi_u32 s2, s1, 0x8000001
	s_mul_i32 s8, s2, 32
	s_sub_u32 s8, s1, s8
	s_mul_i32 s9, s0, 0x2c00000
	s_mul_i32 s28, s2, 0x100000
	s_add_u32 s9, s9, s28
	s_lshl_b32 s8, s8, 8
	s_add_u32 s9, s9, s8
	s_add_u32 s9, s9, 0x5800000
	s_add_u32 s42, s74, s9
	s_addc_u32 s43, s75, 0
	s_mov_b32 m0, s48
	s_add_u32 s49, s48, 0x400
	global_load_lds_dwordx4 v0, s[42:43] nt
	s_mov_b32 m0, s49
	s_add_u32 s49, s48, 0x800
	global_load_lds_dwordx4 v1, s[42:43] nt
	s_mov_b32 m0, s49
	s_add_u32 s49, s48, 0xc00
	global_load_lds_dwordx4 v2, s[42:43] nt
	s_mov_b32 m0, s49
	s_nop 0
	global_load_lds_dwordx4 v3, s[42:43] nt
	global_load_dword v24, v173, s[74:75]
	global_load_dword v24, v173, s[74:75]
	s_add_u32 s47, s40, 1
	s_add_u32 s48, s46, 0x8000
	s_cmp_lt_u32 s47, s53
	s_cbranch_scc0 .Lq5_qdown_pd1
	s_mul_hi_u32 s0, s47, 0x2e8ba3
	s_mul_i32 s1, s0, 1408
	s_sub_u32 s1, s47, s1
	s_mul_hi_u32 s2, s1, 0x8000001
	s_mul_i32 s8, s2, 32
	s_sub_u32 s8, s1, s8
	s_mul_i32 s9, s0, 0x2c00000
	s_mul_i32 s28, s2, 0x100000
	s_add_u32 s9, s9, s28
	s_lshl_b32 s8, s8, 8
	s_add_u32 s9, s9, s8
	s_add_u32 s9, s9, 0x5800000
	s_add_u32 s42, s74, s9
	s_addc_u32 s43, s75, 0
	s_mov_b32 m0, s48
	s_add_u32 s49, s48, 0x400
	global_load_lds_dwordx4 v0, s[42:43] nt
	s_mov_b32 m0, s49
	s_add_u32 s49, s48, 0x800
	global_load_lds_dwordx4 v1, s[42:43] nt
	s_mov_b32 m0, s49
	s_add_u32 s49, s48, 0xc00
	global_load_lds_dwordx4 v2, s[42:43] nt
	s_mov_b32 m0, s49
	s_nop 0
	global_load_lds_dwordx4 v3, s[42:43] nt
	s_branch .Lq5_qdown_pj1

; #define CVT_LOAD(tile_) do { const int k0_ = ((tile_) / ntn) << 7, n0_ = ((tile_) % ntn) << 6; \
;         _Pragma("unroll") for (int pp = 0; pp < 4; ++pp) pv[pp] = *(const float4*)(src + (size_t)(k0_ + lk + 32 * pp) * N + n0_ + ln4); } while (0)
; __device__ __forceinline__ void convT_job(const float* __restrict__ src, bf16_t* __restrict__ dst, int K, int N, int mode, float* t) {
;     ...
;         if (tile + (int)gridDim.x < ntiles) CVT_LOAD(tile + (int)gridDim.x);
.Lq5_qdown_pj1:
	global_load_dword v24, v173, s[74:75]
	global_load_dword v24, v173, s[74:75]
	s_add_u32 s47, s40, 2
	s_add_u32 s48, s46, 0x10000
	s_cmp_lt_u32 s47, s53
	s_cbranch_scc0 .Lq5_qdown_pd2
	s_mul_hi_u32 s0, s47, 0x2e8ba3
	s_mul_i32 s1, s0, 1408
	s_sub_u32 s1, s47, s1
	s_mul_hi_u32 s2, s1, 0x8000001
	s_mul_i32 s8, s2, 32
	s_sub_u32 s8, s1, s8
	s_mul_i32 s9, s0, 0x2c00000
	s_mul_i32 s28, s2, 0x100000
	s_add_u32 s9, s9, s28
	s_lshl_b32 s8, s8, 8
	s_add_u32 s9, s9, s8
	s_add_u32 s9, s9, 0x5800000
	s_add_u32 s42, s74, s9
	s_addc_u32 s43, s75, 0
	s_mov_b32 m0, s48
	s_add_u32 s49, s48, 0x400
	global_load_lds_dwordx4 v0, s[42:43] nt
	s_mov_b32 m0, s49
	s_add_u32 s49, s48, 0x800
	global_load_lds_dwordx4 v1, s[42:43] nt
	s_mov_b32 m0, s49
	s_add_u32 s49, s48, 0xc00
	global_load_lds_dwordx4 v2, s[42:43] nt
	s_mov_b32 m0, s49
	s_nop 0
	global_load_lds_dwordx4 v3, s[42:43] nt
	s_branch .Lq5_qdown_pj2

; #define CVT_LOAD(tile_) do { const int k0_ = ((tile_) / ntn) << 7, n0_ = ((tile_) % ntn) << 6; \
;         _Pragma("unroll") for (int pp = 0; pp < 4; ++pp) pv[pp] = *(const float4*)(src + (size_t)(k0_ + lk + 32 * pp) * N + n0_ + ln4); } while (0)
; __device__ __forceinline__ void convT_job(const float* __restrict__ src, bf16_t* __restrict__ dst, int K, int N, int mode, float* t) {
;     ...
; #pragma unroll 1
;     for (; tile < ntiles; tile += gridDim.x) {
;         const int k0 = (tile / ntn) << 7, n0 = (tile % ntn) << 6;
; #pragma unroll
;         for (int pp = 0; pp < 4; ++pp) { const int k = lk + 32 * pp; t[k * 65 + ln4] = pv[pp].x; t[k * 65 + ln4 + 1] = pv[pp].y; t[k * 65 + ln4 + 2] = pv[pp].z; t[k * 65 + ln4 + 3] = pv[pp].w; }
;         if (tile + (int)gridDim.x < ntiles) CVT_LOAD(tile + (int)gridDim.x);
.Lq5_qdown_loop:
	s_waitcnt vmcnt(14)
	s_barrier
	s_add_u32 s47, s40, 3
	s_add_u32 s48, s41, 0x18000
	s_and_b32 s48, s48, 0x1ffff
	s_add_u32 s48, s48, s46
	s_cmp_lt_u32 s47, s53
	s_cbranch_scc0 .Lq5_qdown_ld
	s_mul_hi_u32 s0, s47, 0x2e8ba3
	s_mul_i32 s1, s0, 1408
	s_sub_u32 s1, s47, s1
	s_mul_hi_u32 s2, s1, 0x8000001
	s_mul_i32 s8, s2, 32
	s_sub_u32 s8, s1, s8
	s_mul_i32 s9, s0, 0x2c00000
	s_mul_i32 s28, s2, 0x100000
	s_add_u32 s9, s9, s28
	s_lshl_b32 s8, s8, 8
	s_add_u32 s9, s9, s8
	s_add_u32 s9, s9, 0x5800000
	s_add_u32 s42, s74, s9
	s_addc_u32 s43, s75, 0
	s_mov_b32 m0, s48
	s_add_u32 s49, s48, 0x400
	global_load_lds_dwordx4 v0, s[42:43] nt
	s_mov_b32 m0, s49
	s_add_u32 s49, s48, 0x800
	global_load_lds_dwordx4 v1, s[42:43] nt
	s_mov_b32 m0, s49
	s_add_u32 s49, s48, 0xc00
	global_load_lds_dwordx4 v2, s[42:43] nt
	s_mov_b32 m0, s49
	s_nop 0
	global_load_lds_dwordx4 v3, s[42:43] nt
	s_branch .Lq5_qdown_lj

; __device__ __forceinline__ unsigned cvt_pk_bf16(float lo, float hi) { unsigned r; asm volatile("v_cvt_pk_bf16_f32 %0, %1, %2" : "=v"(r) : "v"(lo), "v"(hi)); return r; }
; __device__ __forceinline__ void lds_barrier() { asm volatile("s_waitcnt lgkmcnt(0)" ::: "memory"); __builtin_amdgcn_s_barrier(); asm volatile("" ::: "memory"); }
; __device__ __forceinline__ void convT_job(const float* __restrict__ src, bf16_t* __restrict__ dst, int K, int N, int mode, float* t) {
;     ...
;         lds_barrier();
;         const int n = tid >> 3, k16 = (tid & 7) * 16;
;         float v[16];
; #pragma unroll
;         for (int j = 0; j < 16; ++j) v[j] = t[(k16 + j) * 65 + n];
;         const int nn = n0 + n;
;         const int row = mode == 0 ? nn : (256 * (nn >> 7) + (nn & 127) + (mode == 2 ? 128 : 0));
;         u32x4 w0, w1; w0.x = cvt_pk_bf16(v[0], v[1]); w0.y = cvt_pk_bf16(v[2], v[3]); w0.z = cvt_pk_bf16(v[4], v[5]); w0.w = cvt_pk_bf16(v[6], v[7]);
;         w1.x = cvt_pk_bf16(v[8], v[9]); w1.y = cvt_pk_bf16(v[10], v[11]); w1.z = cvt_pk_bf16(v[12], v[13]); w1.w = cvt_pk_bf16(v[14], v[15]);
;         bf16_t* d = dst + (size_t)row * K + k0 + k16;
;         *(u32x4*)d = w0; *(u32x4*)(d + 8) = w1;
;         lds_barrier();
.Lq5_qdown_lj:
	v_add_u32_e32 v7, s41, v4
	ds_read2st64_b32 v[8:9], v7 offset0:0 offset1:1
	ds_read2st64_b32 v[10:11], v7 offset0:2 offset1:3
	ds_read2st64_b32 v[12:13], v7 offset0:4 offset1:5
	ds_read2st64_b32 v[14:15], v7 offset0:6 offset1:7
	ds_read2st64_b32 v[16:17], v7 offset0:8 offset1:9
	ds_read2st64_b32 v[18:19], v7 offset0:10 offset1:11
	ds_read2st64_b32 v[20:21], v7 offset0:12 offset1:13
	ds_read2st64_b32 v[22:23], v7 offset0:14 offset1:15
	s_mul_hi_u32 s0, s40, 0x2e8ba3
	s_mul_i32 s1, s0, 1408
	s_sub_u32 s1, s40, s1
	s_mul_hi_u32 s2, s1, 0x8000001
	s_mul_i32 s8, s2, 32
	s_sub_u32 s8, s1, s8
	s_lshl_b32 s9, s8, 6
	s_mul_i32 s9, s9, 0x2c00
	s_mul_i32 s28, s0, 0x1600000
	s_add_u32 s9, s9, s28
	s_lshl_b32 s2, s2, 8
	s_add_u32 s9, s9, s2
	s_add_u32 s9, s9, 0xdc08000
	s_add_u32 s44, s54, s9
	s_addc_u32 s45, s55, 0
	s_waitcnt lgkmcnt(6)
	v_cvt_pk_bf16_f32 v8, v8, v9
	v_cvt_pk_bf16_f32 v9, v10, v11
	s_waitcnt lgkmcnt(4)
	v_cvt_pk_bf16_f32 v10, v12, v13
	v_cvt_pk_bf16_f32 v11, v14, v15
	s_waitcnt lgkmcnt(2)
	v_cvt_pk_bf16_f32 v12, v16, v17
	v_cvt_pk_bf16_f32 v13, v18, v19
	s_waitcnt lgkmcnt(0)
	v_cvt_pk_bf16_f32 v14, v20, v21
	v_cvt_pk_bf16_f32 v15, v22, v23
	global_store_dwordx4 v5, v[8:11], s[44:45]
	global_store_dwordx4 v5, v[12:15], s[44:45] offset:16
	s_add_u32 s40, s40, 1
	s_add_u32 s41, s41, 0x8000
	s_and_b32 s41, s41, 0x1ffff
	s_cmp_lt_u32 s40, s53
	s_cbranch_scc1 .Lq5_qdown_loop

; __device__ __forceinline__ int opaque_tid() { int t = threadIdx.x; asm volatile("" : "+v"(t)); return t; }
; #define CVT_LOAD(tile_) do { const int k0_ = ((tile_) / ntn) << 7, n0_ = ((tile_) % ntn) << 6; \
;         _Pragma("unroll") for (int pp = 0; pp < 4; ++pp) pv[pp] = *(const float4*)(src + (size_t)(k0_ + lk + 32 * pp) * N + n0_ + ln4); } while (0)
; __device__ __forceinline__ void convT_job(const float* __restrict__ src, bf16_t* __restrict__ dst, int K, int N, int mode, float* t) {
;     const int tid = opaque_tid(), ntn = N >> 6, ntiles = (K >> 7) * ntn;
;     const int lk = tid >> 4, ln4 = (tid & 15) * 4;
;     float4 pv[4];
;     ...
;     int tile = blockIdx.x;
;     if (tile < ntiles) CVT_LOAD(tile);
; __device__ __forceinline__ void phase_convert(const Params& p, unsigned char* smem) {
;     ...
;         convT_job(p.in[6] + (size_t)l * 2048 * 5632, (bf16_t*)(p.ws + OFF_IN + (size_t)l * SZ_IN), 2048, 5632, 0, t);
.Lq5_n2:
	s_cmp_eq_u32 s52, 3
	s_cbranch_scc0 .Lq5_n3
	v_mov_b32_e32 v29, 0x5800
	v_mov_b32_e32 v28, 0x1000
	v_mad_u32_u24 v0, v30, v29, v31
	v_mad_u32_u24 v5, v26, v28, v27
	v_add_u32_e32 v1, 0x16000, v0
	v_add_u32_e32 v2, 0x2c000, v0
	v_add_u32_e32 v3, 0x42000, v0
	s_barrier
	s_mov_b32 s41, 0
	s_mov_b32 s47, s40
	s_mov_b32 s48, s46
	s_mul_hi_u32 s0, s47, 0x2e8ba3
	s_mul_i32 s1, s0, 1408
	s_sub_u32 s1, s47, s1
	s_mul_hi_u32 s2, s1, 0x2e8ba2f
	s_mul_i32 s8, s2, 88
	s_sub_u32 s8, s1, s8
	s_mul_i32 s9, s0, 0x2c00000
	s_mul_i32 s28, s2, 0x2c0000
	s_add_u32 s9, s9, s28
	s_lshl_b32 s8, s8, 8
	s_add_u32 s9, s9, s8
	s_add_u32 s9, s9, 0x2c00000
	s_add_u32 s42, s76, s9
	s_addc_u32 s43, s77, 0
	s_mov_b32 m0, s48
	s_add_u32 s49, s48, 0x400
	global_load_lds_dwordx4 v0, s[42:43] nt
	s_mov_b32 m0, s49
	s_add_u32 s49, s48, 0x800
	global_load_lds_dwordx4 v1, s[42:43] nt
	s_mov_b32 m0, s49
	s_add_u32 s49, s48, 0xc00
	global_load_lds_dwordx4 v2, s[42:43] nt
	s_mov_b32 m0, s49
	s_nop 0
	global_load_lds_dwordx4 v3, s[42:43] nt
	global_load_dword v24, v173, s[76:77]
	global_load_dword v24, v173, s[76:77]
	s_add_u32 s47, s40, 1
	s_add_u32 s48, s46, 0x8000
	s_cmp_lt_u32 s47, s53
	s_cbranch_scc0 .Lq5_qwin_pd1
	s_mul_hi_u32 s0, s47, 0x2e8ba3
	s_mul_i32 s1, s0, 1408
	s_sub_u32 s1, s47, s1
	s_mul_hi_u32 s2, s1, 0x2e8ba2f
	s_mul_i32 s8, s2, 88
	s_sub_u32 s8, s1, s8
	s_mul_i32 s9, s0, 0x2c00000
	s_mul_i32 s28, s2, 0x2c0000
	s_add_u32 s9, s9, s28
	s_lshl_b32 s8, s8, 8
	s_add_u32 s9, s9, s8
	s_add_u32 s9, s9, 0x2c00000
	s_add_u32 s42, s76, s9
	s_addc_u32 s43, s77, 0
	s_mov_b32 m0, s48
	s_add_u32 s49, s48, 0x400
	global_load_lds_dwordx4 v0, s[42:43] nt
	s_mov_b32 m0, s49
	s_add_u32 s49, s48, 0x800
	global_load_lds_dwordx4 v1, s[42:43] nt
	s_mov_b32 m0, s49
	s_add_u32 s49, s48, 0xc00
	global_load_lds_dwordx4 v2, s[42:43] nt
	s_mov_b32 m0, s49
	s_nop 0
	global_load_lds_dwordx4 v3, s[42:43] nt
	s_branch .Lq5_qwin_pj1

; #define CVT_LOAD(tile_) do { const int k0_ = ((tile_) / ntn) << 7, n0_ = ((tile_) % ntn) << 6; \
;         _Pragma("unroll") for (int pp = 0; pp < 4; ++pp) pv[pp] = *(const float4*)(src + (size_t)(k0_ + lk + 32 * pp) * N + n0_ + ln4); } while (0)
; __device__ __forceinline__ void convT_job(const float* __restrict__ src, bf16_t* __restrict__ dst, int K, int N, int mode, float* t) {
;     ...
;         if (tile + (int)gridDim.x < ntiles) CVT_LOAD(tile + (int)gridDim.x);
.Lq5_qwin_pj1:
	global_load_dword v24, v173, s[76:77]
	global_load_dword v24, v173, s[76:77]
	s_add_u32 s47, s40, 2
	s_add_u32 s48, s46, 0x10000
	s_cmp_lt_u32 s47, s53
	s_cbranch_scc0 .Lq5_qwin_pd2
	s_mul_hi_u32 s0, s47, 0x2e8ba3
	s_mul_i32 s1, s0, 1408
	s_sub_u32 s1, s47, s1
	s_mul_hi_u32 s2, s1, 0x2e8ba2f
	s_mul_i32 s8, s2, 88
	s_sub_u32 s8, s1, s8
	s_mul_i32 s9, s0, 0x2c00000
	s_mul_i32 s28, s2, 0x2c0000
	s_add_u32 s9, s9, s28
	s_lshl_b32 s8, s8, 8
	s_add_u32 s9, s9, s8
	s_add_u32 s9, s9, 0x2c00000
	s_add_u32 s42, s76, s9
	s_addc_u32 s43, s77, 0
	s_mov_b32 m0, s48
	s_add_u32 s49, s48, 0x400
	global_load_lds_dwordx4 v0, s[42:43] nt
	s_mov_b32 m0, s49
	s_add_u32 s49, s48, 0x800
	global_load_lds_dwordx4 v1, s[42:43] nt
	s_mov_b32 m0, s49
	s_add_u32 s49, s48, 0xc00
	global_load_lds_dwordx4 v2, s[42:43] nt
	s_mov_b32 m0, s49
	s_nop 0
	global_load_lds_dwordx4 v3, s[42:43] nt
	s_branch .Lq5_qwin_pj2

; #define CVT_LOAD(tile_) do { const int k0_ = ((tile_) / ntn) << 7, n0_ = ((tile_) % ntn) << 6; \
;         _Pragma("unroll") for (int pp = 0; pp < 4; ++pp) pv[pp] = *(const float4*)(src + (size_t)(k0_ + lk + 32 * pp) * N + n0_ + ln4); } while (0)
; __device__ __forceinline__ void convT_job(const float* __restrict__ src, bf16_t* __restrict__ dst, int K, int N, int mode, float* t) {
;     ...
;     int tile = blockIdx.x;
;     if (tile < ntiles) CVT_LOAD(tile);
; #pragma unroll 1
;     for (; tile < ntiles; tile += gridDim.x) {
;         const int k0 = (tile / ntn) << 7, n0 = (tile % ntn) << 6;
; #pragma unroll
;         for (int pp = 0; pp < 4; ++pp) { const int k = lk + 32 * pp; t[k * 65 + ln4] = pv[pp].x; t[k * 65 + ln4 + 1] = pv[pp].y; t[k * 65 + ln4 + 2] = pv[pp].z; t[k * 65 + ln4 + 3] = pv[pp].w; }
;         if (tile + (int)gridDim.x < ntiles) CVT_LOAD(tile + (int)gridDim.x);
; __device__ __forceinline__ void phase_convert(const Params& p, unsigned char* smem) {
;     ...
;         convT_job(p.in[6] + (size_t)l * 2048 * 5632, (bf16_t*)(p.ws + OFF_IN + (size_t)l * SZ_IN), 2048, 5632, 0, t);
.Lq5_qwin_loop:
	s_waitcnt vmcnt(14)
	s_barrier
	s_add_u32 s47, s40, 3
	s_add_u32 s48, s41, 0x18000
	s_and_b32 s48, s48, 0x1ffff
	s_add_u32 s48, s48, s46
	s_cmp_lt_u32 s47, s53
	s_cbranch_scc0 .Lq5_qwin_ld
	s_mul_hi_u32 s0, s47, 0x2e8ba3
	s_mul_i32 s1, s0, 1408
	s_sub_u32 s1, s47, s1
	s_mul_hi_u32 s2, s1, 0x2e8ba2f
	s_mul_i32 s8, s2, 88
	s_sub_u32 s8, s1, s8
	s_mul_i32 s9, s0, 0x2c00000
	s_mul_i32 s28, s2, 0x2c0000
	s_add_u32 s9, s9, s28
	s_lshl_b32 s8, s8, 8
	s_add_u32 s9, s9, s8
	s_add_u32 s9, s9, 0x2c00000
	s_add_u32 s42, s76, s9
	s_addc_u32 s43, s77, 0
	s_mov_b32 m0, s48
	s_add_u32 s49, s48, 0x400
	global_load_lds_dwordx4 v0, s[42:43] nt
	s_mov_b32 m0, s49
	s_add_u32 s49, s48, 0x800
	global_load_lds_dwordx4 v1, s[42:43] nt
	s_mov_b32 m0, s49
	s_add_u32 s49, s48, 0xc00
	global_load_lds_dwordx4 v2, s[42:43] nt
	s_mov_b32 m0, s49
	s_nop 0
	global_load_lds_dwordx4 v3, s[42:43] nt
	s_branch .Lq5_qwin_lj

; __device__ __forceinline__ unsigned cvt_pk_bf16(float lo, float hi) { unsigned r; asm volatile("v_cvt_pk_bf16_f32 %0, %1, %2" : "=v"(r) : "v"(lo), "v"(hi)); return r; }
; __device__ __forceinline__ void lds_barrier() { asm volatile("s_waitcnt lgkmcnt(0)" ::: "memory"); __builtin_amdgcn_s_barrier(); asm volatile("" ::: "memory"); }
; __device__ __forceinline__ void convT_job(const float* __restrict__ src, bf16_t* __restrict__ dst, int K, int N, int mode, float* t) {
;     ...
;         const int n = tid >> 3, k16 = (tid & 7) * 16;
;         float v[16];
; #pragma unroll
;         for (int j = 0; j < 16; ++j) v[j] = t[(k16 + j) * 65 + n];
;         const int nn = n0 + n;
;         const int row = mode == 0 ? nn : (256 * (nn >> 7) + (nn & 127) + (mode == 2 ? 128 : 0));
;         u32x4 w0, w1; w0.x = cvt_pk_bf16(v[0], v[1]); w0.y = cvt_pk_bf16(v[2], v[3]); w0.z = cvt_pk_bf16(v[4], v[5]); w0.w = cvt_pk_bf16(v[6], v[7]);
;         w1.x = cvt_pk_bf16(v[8], v[9]); w1.y = cvt_pk_bf16(v[10], v[11]); w1.z = cvt_pk_bf16(v[12], v[13]); w1.w = cvt_pk_bf16(v[14], v[15]);
;         bf16_t* d = dst + (size_t)row * K + k0 + k16;
;         *(u32x4*)d = w0; *(u32x4*)(d + 8) = w1;
;         lds_barrier();
; __device__ __forceinline__ void phase_convert(const Params& p, unsigned char* smem) {
;     ...
;         convT_job(p.in[6] + (size_t)l * 2048 * 5632, (bf16_t*)(p.ws + OFF_IN + (size_t)l * SZ_IN), 2048, 5632, 0, t);
.Lq5_qwin_lj:
	v_add_u32_e32 v7, s41, v4
	ds_read2st64_b32 v[8:9], v7 offset0:0 offset1:1
	ds_read2st64_b32 v[10:11], v7 offset0:2 offset1:3
	ds_read2st64_b32 v[12:13], v7 offset0:4 offset1:5
	ds_read2st64_b32 v[14:15], v7 offset0:6 offset1:7
	ds_read2st64_b32 v[16:17], v7 offset0:8 offset1:9
	ds_read2st64_b32 v[18:19], v7 offset0:10 offset1:11
	ds_read2st64_b32 v[20:21], v7 offset0:12 offset1:13
	ds_read2st64_b32 v[22:23], v7 offset0:14 offset1:15
	s_mul_hi_u32 s0, s40, 0x2e8ba3
	s_mul_i32 s1, s0, 1408
	s_sub_u32 s1, s40, s1
	s_mul_hi_u32 s2, s1, 0x2e8ba2f
	s_mul_i32 s8, s2, 88
	s_sub_u32 s8, s1, s8
	s_lshl_b32 s9, s8, 6
	s_mul_i32 s9, s9, 0x1000
	s_mul_i32 s28, s0, 0x1600000
	s_add_u32 s9, s9, s28
	s_lshl_b32 s2, s2, 8
	s_add_u32 s9, s9, s2
	s_add_u32 s9, s9, 0x11e08000
	s_add_u32 s44, s54, s9
	s_addc_u32 s45, s55, 0
	s_waitcnt lgkmcnt(6)
	v_cvt_pk_bf16_f32 v8, v8, v9
	v_cvt_pk_bf16_f32 v9, v10, v11
	s_waitcnt lgkmcnt(4)
	v_cvt_pk_bf16_f32 v10, v12, v13
	v_cvt_pk_bf16_f32 v11, v14, v15
	s_waitcnt lgkmcnt(2)
	v_cvt_pk_bf16_f32 v12, v16, v17
	v_cvt_pk_bf16_f32 v13, v18, v19
	s_waitcnt lgkmcnt(0)
	v_cvt_pk_bf16_f32 v14, v20, v21
	v_cvt_pk_bf16_f32 v15, v22, v23
	global_store_dwordx4 v5, v[8:11], s[44:45]
	global_store_dwordx4 v5, v[12:15], s[44:45] offset:16
	s_add_u32 s40, s40, 1
	s_add_u32 s41, s41, 0x8000
	s_and_b32 s41, s41, 0x1ffff
	s_cmp_lt_u32 s40, s53
	s_cbranch_scc1 .Lq5_qwin_loop

; __device__ __forceinline__ void run_phase(const Params& p, int ph, unsigned char* smem, int rep) {
;     ...
;         for (;;) {
;             __syncthreads();
;             if (threadIdx.x == 0) *s_item = (int)atomicAdd(ctr, 1u);
;             __syncthreads();
;             const int it = *s_item;
;             if (it >= 784) break;
.Lq5_n3:
.Lq5_done:
	v_readlane_b32 s52, v255, 46
	v_readlane_b32 s53, v255, 47
	v_readlane_b32 s54, v255, 4
	s_branch .LBB0_129

; __device__ __forceinline__ int opaque_tid() { int t = threadIdx.x; asm volatile("" : "+v"(t)); return t; }
; __device__ __forceinline__ void rgpost_item(const Params& p, int item, unsigned char* smem) {
;     const int tid = opaque_tid(), c4 = (tid & 127) * 4, sg = tid >> 7, b = item >> 6, tau = item & 63;
;     const bf16_t* P = (const bf16_t*)(p.ws + OFF_H);
;     bf16_t* Y = (bf16_t*)(p.ws + OFF_XB);
;     const float* AT = (const float*)(p.ws + OFF_ATILE) + (size_t)b * 64 * 512 + c4; const float* HT = (const float*)(p.ws + OFF_HTILE) + (size_t)b * 64 * 512 + c4;
;     const float* HL = (const float*)((unsigned char*)p.out + OUT_HLOC); const float* CA = (const float*)((unsigned char*)p.out + OUT_CUMA);
;     f32x4 pa = {1.f, 1.f, 1.f, 1.f}, ph = {0.f, 0.f, 0.f, 0.f};
;     {
;         const int sbeg = sg * 16, send = tau < sbeg + 16 ? tau : sbeg + 16;
; #pragma unroll 1
;         for (int s0 = sbeg; s0 < send; s0 += 8) {
;             f32x4 av[8], hv[8];
; #pragma unroll
;             for (int i = 0; i < 8; ++i) { const bool ok = s0 + i < send; av[i] = ok ? *(const f32x4*)(AT + (s0 + i) * 512) : (f32x4){1.f, 1.f, 1.f, 1.f}; hv[i] = ok ? *(const f32x4*)(HT + (s0 + i) * 512) : (f32x4){0.f, 0.f, 0.f, 0.f}; }
; __device__ __forceinline__ void run_phase(const Params& p, int ph, unsigned char* smem, int rep) {
;     ...
;         for (;;) {
;             __syncthreads();
;             if (threadIdx.x == 0) *s_item = (int)atomicAdd(ctr, 1u);
;             __syncthreads();
;             const int it = *s_item;
;             if (it >= 784) break;
;     ...
;             if (rep == 1 && !((PROBE_SUB == 1 && it < 16) || (PROBE_SUB == 2 && it >= 16 && it < 528) || (PROBE_SUB == 3 && it >= 528) || (PROBE_SUB == 4 && it >= 16))) continue;
;     ...
;             if (it < 16) hgrn_item(p, l, it, smem, rep);
;             else if (it < 528) attn_item(p, it - 16, smem);
;             else rgpost_item(p, it - 528, smem);
.LBB0_135:
	s_or_b64 exec, exec, s[0:1]
	v_mov_b32_e32 v0, s54
	s_waitcnt lgkmcnt(0)
	s_barrier
	ds_read_b32 v0, v0
	v_readlane_b32 s1, v255, 33
	s_movk_i32 s0, 0x30f
	s_cmp_eq_u32 s1, 0
	s_cselect_b32 s0, 0x46f, s0
	s_waitcnt lgkmcnt(0)
	v_cmp_lt_i32_e32 vcc, s0, v0
	v_readfirstlane_b32 s50, v0
	s_mov_b64 s[0:1], -1
	s_cbranch_vccnz .LBB0_130
	s_cmp_gt_i32 s50, 15
	s_cbranch_scc0 .LBB0_223
	s_cmpk_gt_u32 s50, 0x20f
	s_cbranch_scc0 .LBB0_160
	s_cmpk_gt_u32 s50, 0x30f
	s_cbranch_scc1 .Lq5_conv
	v_mov_b32_e32 v81, v234
	s_add_i32 s0, s50, 0xfffffdf0
	s_and_b32 s8, s0, 63
	v_and_b32_e32 v73, 0x7f, v81
	v_ashrrev_i32_e32 v8, 3, v81
	v_lshlrev_b32_e32 v80, 2, v73
	v_and_b32_e32 v72, -16, v8
	v_mov_b32_e32 v3, 0
	v_mov_b32_e32 v7, 1.0
	s_lshr_b32 s2, s0, 6
	v_cmp_gt_i32_e32 vcc, s8, v72
	v_lshlrev_b32_e32 v172, 2, v80
	v_mov_b32_e32 v6, v7
	v_mov_b32_e32 v5, v7
	v_mov_b32_e32 v4, v7
	v_mov_b32_e32 v2, v3
	v_mov_b32_e32 v1, v3
	v_mov_b32_e32 v0, v3
	s_and_saveexec_b64 s[0:1], vcc
	s_cbranch_execz .LBB0_158
	s_lshl_b64 s[28:29], s[2:3], 17
	v_readlane_b32 s26, v253, 43
	v_readlane_b32 s27, v253, 44
	s_add_u32 s40, s26, s28
	s_addc_u32 s41, s27, s29
	v_readlane_b32 s26, v253, 45
	v_add_u32_e32 v0, 16, v72
	v_readlane_b32 s27, v253, 46
	s_add_u32 s28, s26, s28
	v_min_i32_e32 v82, s8, v0
	v_lshlrev_b32_e32 v0, 9, v8
	s_addc_u32 s29, s27, s29
	v_and_b32_e32 v78, 0xffffe000, v0
	v_mov_b32_e32 v0, 0
	v_mov_b32_e32 v4, 1.0
	v_lshl_add_u64 v[74:75], s[40:41], 0, v[172:173]
	v_lshl_add_u64 v[76:77], s[28:29], 0, v[172:173]
	s_mov_b64 s[40:41], 0
	v_mov_b32_e32 v83, v72
	v_mov_b32_e32 v5, v4
	v_mov_b32_e32 v6, v4
	v_mov_b32_e32 v7, v4
	v_mov_b32_e32 v1, v0
	v_mov_b32_e32 v2, v0
	v_mov_b32_e32 v3, v0
	s_branch .LBB0_141

.LBB0_271:
	s_add_i32 s26, s46, -6
	s_and_b32 s53, s26, 1
	s_mul_i32 s26, s53, 0x4400
	s_add_i32 s56, s26, 0
	s_lshl_b32 s26, s53, 10
	s_xor_b64 s[8:9], s[42:43], -1
	s_add_i32 s55, s56, s26
	s_and_saveexec_b64 s[40:41], s[8:9]
	s_cbranch_execz .LBB0_273
	v_add3_u32 v136, s56, v102, v115
	ds_read_b128 v[96:99], v136
	ds_read_b128 v[120:123], v136 offset:64
	v_and_b32_e32 v201, 1, v118
	v_mov_b32_e32 v200, 0x80000000
	v_cmp_eq_u32_e32 vcc, 1, v201
	v_mov_b32_e32 v201, 0x7fffffff
	s_nop 0
	v_cndmask_b32_e32 v200, v200, v201, vcc
	v_cndmask_b32_e64 v200, v100, v200, s[0:1]
	v_add_u32_e32 v119, v119, v104
	v_cmp_le_i32_e32 vcc, v119, v200
	s_waitcnt lgkmcnt(1)
	v_mfma_f32_16x16x32_bf16 v[96:99], v[96:99], v[0:3], 0
	ds_read_b128 v[124:127], v136 offset:4416
	ds_read_b128 v[128:131], v136 offset:8768
	ds_read_b128 v[132:135], v136 offset:13120
	s_waitcnt lgkmcnt(3)
	v_mfma_f32_16x16x32_bf16 v[96:99], v[120:123], v[4:7], v[96:99]
	ds_read_b128 v[120:123], v136 offset:128
	s_waitcnt lgkmcnt(0)
	v_mfma_f32_16x16x32_bf16 v[96:99], v[120:123], v[8:11], v[96:99]
	ds_read_b128 v[120:123], v136 offset:192
	s_waitcnt lgkmcnt(0)
	v_mfma_f32_16x16x32_bf16 v[120:123], v[120:123], v[12:15], v[96:99]
	s_nop 4
	ds_read_b128 v[96:99], v136 offset:4352
	s_nop 1
	v_mul_f32_e32 v120, 0x3e0293ee, v120
	v_mul_f32_e32 v121, 0x3e0293ee, v121
	v_mul_f32_e32 v122, 0x3e0293ee, v122
	s_waitcnt lgkmcnt(0)
	v_mfma_f32_16x16x32_bf16 v[96:99], v[96:99], v[0:3], 0
	v_mul_f32_e32 v123, 0x3e0293ee, v123
	v_mfma_f32_16x16x32_bf16 v[96:99], v[124:127], v[4:7], v[96:99]
	ds_read_b128 v[124:127], v136 offset:4480
	s_waitcnt lgkmcnt(0)
	v_mfma_f32_16x16x32_bf16 v[96:99], v[124:127], v[8:11], v[96:99]
	ds_read_b128 v[124:127], v136 offset:4544
	s_waitcnt lgkmcnt(0)
	v_mfma_f32_16x16x32_bf16 v[124:127], v[124:127], v[12:15], v[96:99]
	s_nop 4
	ds_read_b128 v[96:99], v136 offset:8704
	s_nop 1
	v_mul_f32_e32 v124, 0x3e0293ee, v124
	s_waitcnt lgkmcnt(0)
	v_mfma_f32_16x16x32_bf16 v[96:99], v[96:99], v[0:3], 0
	v_mul_f32_e32 v125, 0x3e0293ee, v125
	v_mul_f32_e32 v126, 0x3e0293ee, v126
	v_mul_f32_e32 v127, 0x3e0293ee, v127
	v_mfma_f32_16x16x32_bf16 v[96:99], v[128:131], v[4:7], v[96:99]
	ds_read_b128 v[128:131], v136 offset:8832
	s_waitcnt lgkmcnt(0)
	v_mfma_f32_16x16x32_bf16 v[96:99], v[128:131], v[8:11], v[96:99]
	ds_read_b128 v[128:131], v136 offset:8896
	s_waitcnt lgkmcnt(0)
	v_mfma_f32_16x16x32_bf16 v[128:131], v[128:131], v[12:15], v[96:99]
	s_nop 4
	ds_read_b128 v[96:99], v136 offset:13056
	s_nop 1
	v_mul_f32_e32 v128, 0x3e0293ee, v128
	s_waitcnt lgkmcnt(0)
	v_mfma_f32_16x16x32_bf16 v[96:99], v[96:99], v[0:3], 0
	v_mul_f32_e32 v129, 0x3e0293ee, v129
	v_mul_f32_e32 v130, 0x3e0293ee, v130
	v_mul_f32_e32 v131, 0x3e0293ee, v131
	v_mfma_f32_16x16x32_bf16 v[96:99], v[132:135], v[4:7], v[96:99]
	ds_read_b128 v[132:135], v136 offset:13184
	s_waitcnt lgkmcnt(0)
	v_mfma_f32_16x16x32_bf16 v[96:99], v[132:135], v[8:11], v[96:99]
	ds_read_b128 v[132:135], v136 offset:13248
	s_waitcnt lgkmcnt(0)
	v_mfma_f32_16x16x32_bf16 v[96:99], v[132:135], v[12:15], v[96:99]
	s_nop 3
	v_add_u32_e32 v133, 2, v119
	s_nop 2
	v_mul_f32_e32 v96, 0x3e0293ee, v96
	v_cndmask_b32_e32 v120, v238, v120, vcc
	v_cmp_lt_i32_e32 vcc, v119, v200
	v_mul_f32_e32 v97, 0x3e0293ee, v97
	v_mul_f32_e32 v98, 0x3e0293ee, v98
	s_nop 3
	v_mul_f32_e32 v99, 0x3e0293ee, v99
	s_nop 0
	v_cndmask_b32_e32 v121, v238, v121, vcc
	v_cmp_le_i32_e32 vcc, v133, v200
	v_max3_f32 v132, v117, v120, v121
	s_nop 0
	v_add_u32_e32 v133, 3, v119
	s_nop 0
	v_cndmask_b32_e32 v122, v238, v122, vcc
	v_cmp_le_i32_e32 vcc, v133, v200
	s_nop 1
	v_add_u32_e32 v133, 4, v119
	s_nop 0
	v_cndmask_b32_e32 v123, v238, v123, vcc
	v_cmp_le_i32_e32 vcc, v133, v200
	v_max3_f32 v132, v132, v122, v123
	s_nop 0
	v_add_u32_e32 v133, 5, v119
	s_nop 0
	v_cndmask_b32_e32 v124, v238, v124, vcc
	v_cmp_le_i32_e32 vcc, v133, v200
	s_nop 1
	v_add_u32_e32 v133, 6, v119
	s_nop 0
	v_cndmask_b32_e32 v125, v238, v125, vcc
	v_cmp_le_i32_e32 vcc, v133, v200
	v_max3_f32 v132, v132, v124, v125
	s_nop 0
	v_add_u32_e32 v133, 7, v119
	s_nop 0
	v_cndmask_b32_e32 v126, v238, v126, vcc
	v_cmp_le_i32_e32 vcc, v133, v200
	s_nop 1
	v_add_u32_e32 v133, 32, v119
	s_nop 0
	v_cndmask_b32_e32 v127, v238, v127, vcc
	v_cmp_le_i32_e32 vcc, v133, v200
	v_max3_f32 v132, v132, v126, v127
	s_nop 0
	v_add_u32_e32 v133, 33, v119
	s_nop 0
	v_cndmask_b32_e32 v128, v238, v128, vcc
	v_cmp_le_i32_e32 vcc, v133, v200
	s_nop 1
	v_add_u32_e32 v133, 34, v119
	s_nop 0
	v_cndmask_b32_e32 v129, v238, v129, vcc
	v_cmp_le_i32_e32 vcc, v133, v200
	v_max3_f32 v132, v132, v128, v129
	s_nop 0
	v_add_u32_e32 v133, 35, v119
	s_nop 0
	v_cndmask_b32_e32 v130, v238, v130, vcc
	v_cmp_le_i32_e32 vcc, v133, v200
	s_nop 1
	v_add_u32_e32 v133, 36, v119
	s_nop 0
	v_cndmask_b32_e32 v131, v238, v131, vcc
	v_cmp_le_i32_e32 vcc, v133, v200
	v_max3_f32 v132, v132, v130, v131
	s_nop 0
	v_add_u32_e32 v133, 37, v119
	s_nop 0
	v_cndmask_b32_e32 v96, v238, v96, vcc
	v_cmp_le_i32_e32 vcc, v133, v200
	s_nop 1
	s_nop 1
	v_cndmask_b32_e32 v133, v238, v97, vcc
	v_max3_f32 v97, v132, v96, v133
	v_add_u32_e32 v132, 38, v119
	v_cmp_le_i32_e32 vcc, v132, v200
	v_add_u32_e32 v119, 39, v119
	s_nop 0
	s_nop 1
	v_cndmask_b32_e32 v98, v238, v98, vcc
	v_cmp_le_i32_e32 vcc, v119, v200
	s_nop 1
	v_and_b32_e32 v119, 64, v239
	v_xor_b32_e32 v118, 16, v239
	v_add_u32_e32 v119, 64, v119
	v_cndmask_b32_e32 v99, v238, v99, vcc
	v_cmp_lt_i32_e32 vcc, v118, v119
	v_max3_f32 v97, v97, v98, v99
	s_nop 0
	v_cndmask_b32_e32 v118, v239, v118, vcc
	v_lshlrev_b32_e32 v118, 2, v118
	ds_bpermute_b32 v118, v118, v97
	s_waitcnt lgkmcnt(0)
	v_max_f32_e32 v118, v118, v118
	v_max_f32_e32 v97, v97, v118
	v_xor_b32_e32 v118, 32, v239
	v_cmp_lt_i32_e32 vcc, v118, v119
	s_nop 1
	v_cndmask_b32_e32 v118, v239, v118, vcc
	v_lshlrev_b32_e32 v118, 2, v118
	ds_bpermute_b32 v118, v118, v97
	s_waitcnt lgkmcnt(0)
	v_max_f32_e32 v118, v118, v118
	v_max_f32_e32 v97, v97, v118
	v_sub_f32_e32 v118, v120, v97
	v_exp_f32_e32 v134, v118
	v_sub_f32_e32 v119, v121, v97
	v_exp_f32_e32 v135, v119
	v_sub_f32_e32 v119, v122, v97
	v_exp_f32_e32 v136, v119
	v_sub_f32_e32 v119, v123, v97
	v_exp_f32_e32 v137, v119
	v_sub_f32_e32 v119, v124, v97
	v_add_f32_e32 v118, 0, v134
	v_exp_f32_e32 v138, v119
	v_sub_f32_e32 v119, v125, v97
	v_add_f32_e32 v118, v135, v118
	v_exp_f32_e32 v139, v119
	v_sub_f32_e32 v119, v126, v97
	v_add_f32_e32 v118, v136, v118
	v_exp_f32_e32 v140, v119
	v_sub_f32_e32 v119, v127, v97
	v_add_f32_e32 v118, v137, v118
	v_exp_f32_e32 v141, v119
	v_sub_f32_e32 v119, v128, v97
	v_add_f32_e32 v118, v138, v118
	v_exp_f32_e32 v142, v119
	v_sub_f32_e32 v119, v129, v97
	v_sub_f32_e32 v96, v96, v97
	v_add_f32_e32 v118, v139, v118
	v_exp_f32_e32 v143, v119
	v_sub_f32_e32 v119, v130, v97
	v_exp_f32_e32 v147, v96
	v_sub_f32_e32 v96, v133, v97
	v_add_f32_e32 v118, v140, v118
	v_exp_f32_e32 v144, v119
	v_sub_f32_e32 v119, v131, v97
	v_exp_f32_e32 v148, v96
	v_sub_f32_e32 v96, v98, v97
	v_sub_f32_e32 v117, v117, v97
	v_add_f32_e32 v118, v141, v118
	v_exp_f32_e32 v145, v119
	v_exp_f32_e32 v149, v96
	v_sub_f32_e32 v96, v99, v97
	v_add_f32_e32 v118, v142, v118
	v_exp_f32_e32 v99, v96
	v_exp_f32_e32 v96, v117
	v_add_f32_e32 v118, v143, v118
	v_add_f32_e32 v118, v144, v118
	v_add_f32_e32 v146, v145, v118
	v_pk_mul_f32 v[130:131], v[76:77], v[96:97] op_sel_hi:[1,0]
	v_pk_mul_f32 v[76:77], v[80:81], v[96:97] op_sel_hi:[1,0]
	v_add_f32_e32 v80, v147, v146
	v_add_f32_e32 v80, v148, v80
	v_add_f32_e32 v80, v149, v80
	v_add3_u32 v117, s55, v102, v116
	v_pk_mul_f32 v[124:125], v[70:71], v[96:97] op_sel_hi:[1,0]
	v_pk_mul_f32 v[122:123], v[68:69], v[96:97] op_sel_hi:[1,0]
	v_pk_mul_f32 v[128:129], v[74:75], v[96:97] op_sel_hi:[1,0]
	v_pk_mul_f32 v[126:127], v[72:73], v[96:97] op_sel_hi:[1,0]
	v_pk_mul_f32 v[132:133], v[78:79], v[96:97] op_sel_hi:[1,0]
	v_pk_mul_f32 v[78:79], v[82:83], v[96:97] op_sel_hi:[1,0]
	v_pk_mul_f32 v[74:75], v[86:87], v[96:97] op_sel_hi:[1,0]
	v_pk_mul_f32 v[72:73], v[84:85], v[96:97] op_sel_hi:[1,0]
	v_pk_mul_f32 v[70:71], v[90:91], v[96:97] op_sel_hi:[1,0]
	v_pk_mul_f32 v[68:69], v[88:89], v[96:97] op_sel_hi:[1,0]
	v_add_f32_e32 v98, v99, v80
	v_cvt_pk_bf16_f32 v80, v134, v135
	v_cvt_pk_bf16_f32 v81, v136, v137
	v_cvt_pk_bf16_f32 v82, v138, v139
	v_cvt_pk_bf16_f32 v83, v140, v141
	ds_read_b128 v[84:87], v117 offset:34816
	ds_read_b128 v[88:91], v117 offset:37120
	s_waitcnt lgkmcnt(0)
	v_mfma_f32_16x16x32_bf16 v[88:91], v[88:91], v[80:83], v[122:125]
	s_nop 2
	ds_read_b128 v[122:125], v117 offset:44032
	v_pk_mul_f32 v[120:121], v[66:67], v[96:97] op_sel_hi:[1,0]
	v_pk_mul_f32 v[118:119], v[64:65], v[96:97] op_sel_hi:[1,0]
	v_pk_mul_f32 v[66:67], v[94:95], v[96:97] op_sel_hi:[1,0]
	v_pk_mul_f32 v[64:65], v[92:93], v[96:97] op_sel_hi:[1,0]
	ds_read_b128 v[92:95], v117 offset:39424
	s_waitcnt lgkmcnt(1)
	v_mfma_f32_16x16x32_bf16 v[122:125], v[122:125], v[80:83], v[76:79]
	s_nop 2
	ds_read_b128 v[76:79], v117 offset:46336
	v_fmac_f32_e32 v98, v112, v96
	v_mov_b32_e32 v112, v98
	v_mfma_f32_16x16x32_bf16 v[84:87], v[84:87], v[80:83], v[118:121]
	s_nop 2
	ds_read_b128 v[118:121], v117 offset:41728
	s_waitcnt lgkmcnt(2)
	v_mfma_f32_16x16x32_bf16 v[92:95], v[92:95], v[80:83], v[126:129]
	s_waitcnt lgkmcnt(1)
	v_mfma_f32_16x16x32_bf16 v[126:129], v[76:79], v[80:83], v[72:75]
	s_nop 2
	ds_read_b128 v[72:75], v117 offset:48640
	s_waitcnt lgkmcnt(1)
	v_mfma_f32_16x16x32_bf16 v[118:121], v[118:121], v[80:83], v[130:133]
	s_waitcnt lgkmcnt(0)
	v_mfma_f32_16x16x32_bf16 v[130:133], v[72:75], v[80:83], v[68:71]
	s_nop 2
	ds_read_b128 v[68:71], v117 offset:50944
	v_cvt_pk_bf16_f32 v138, v142, v143
	v_cvt_pk_bf16_f32 v139, v144, v145
	s_waitcnt lgkmcnt(0)
	v_mfma_f32_16x16x32_bf16 v[134:137], v[68:71], v[80:83], v[64:67]
	v_cvt_pk_bf16_f32 v140, v147, v148
	v_cvt_pk_bf16_f32 v141, v149, v99
	s_nop 2
	ds_read_b128 v[64:67], v117 offset:34880
	ds_read_b128 v[68:71], v117 offset:37184
	ds_read_b128 v[72:75], v117 offset:39488
	ds_read_b128 v[76:79], v117 offset:41792
	s_waitcnt lgkmcnt(3)
	v_mfma_f32_16x16x32_bf16 v[64:67], v[64:67], v[138:141], v[84:87]
	ds_read_b128 v[80:83], v117 offset:44096
	s_nop 1
	ds_read_b128 v[84:87], v117 offset:46400
	s_waitcnt lgkmcnt(4)
	v_mfma_f32_16x16x32_bf16 v[68:71], v[68:71], v[138:141], v[88:91]
	s_waitcnt lgkmcnt(3)
	v_mfma_f32_16x16x32_bf16 v[72:75], v[72:75], v[138:141], v[92:95]
	s_nop 0
	ds_read_b128 v[88:91], v117 offset:48704
	s_nop 0
	ds_read_b128 v[92:95], v117 offset:51008
	s_waitcnt lgkmcnt(4)
	v_mfma_f32_16x16x32_bf16 v[76:79], v[76:79], v[138:141], v[118:121]
	v_mov_b32_e32 v117, v97
	s_waitcnt lgkmcnt(3)
	v_mfma_f32_16x16x32_bf16 v[80:83], v[80:83], v[138:141], v[122:125]
	s_waitcnt lgkmcnt(2)
	v_mfma_f32_16x16x32_bf16 v[84:87], v[84:87], v[138:141], v[126:129]
	s_waitcnt lgkmcnt(1)
	v_mfma_f32_16x16x32_bf16 v[88:91], v[88:91], v[138:141], v[130:133]
	s_waitcnt lgkmcnt(0)
	v_mfma_f32_16x16x32_bf16 v[92:95], v[92:95], v[138:141], v[134:137]

.LBB0_281:
	s_mul_i32 s9, s42, 0x4400
	v_add3_u32 v136, v114, s9, v115
	ds_read_b128 v[96:99], v136
	ds_read_b128 v[120:123], v136 offset:64
	v_and_b32_e32 v201, 1, v118
	v_mov_b32_e32 v200, 0x80000000
	v_cmp_eq_u32_e32 vcc, 1, v201
	v_mov_b32_e32 v201, 0x7fffffff
	s_nop 0
	v_cndmask_b32_e32 v200, v200, v201, vcc
	v_cndmask_b32_e64 v200, v100, v200, s[0:1]
	v_add_u32_e32 v119, v119, v104
	v_cmp_le_i32_e32 vcc, v119, v200
	s_mul_i32 s8, s42, 0x4800
	s_waitcnt lgkmcnt(1)
	v_mfma_f32_16x16x32_bf16 v[96:99], v[96:99], v[0:3], 0
	ds_read_b128 v[124:127], v136 offset:4416
	ds_read_b128 v[128:131], v136 offset:8768
	ds_read_b128 v[132:135], v136 offset:13120
	s_waitcnt lgkmcnt(3)
	v_mfma_f32_16x16x32_bf16 v[96:99], v[120:123], v[4:7], v[96:99]
	ds_read_b128 v[120:123], v136 offset:128
	s_waitcnt lgkmcnt(0)
	v_mfma_f32_16x16x32_bf16 v[96:99], v[120:123], v[8:11], v[96:99]
	ds_read_b128 v[120:123], v136 offset:192
	s_waitcnt lgkmcnt(0)
	v_mfma_f32_16x16x32_bf16 v[120:123], v[120:123], v[12:15], v[96:99]
	s_nop 4
	ds_read_b128 v[96:99], v136 offset:4352
	s_nop 1
	v_mul_f32_e32 v120, 0x3e0293ee, v120
	v_mul_f32_e32 v121, 0x3e0293ee, v121
	v_mul_f32_e32 v122, 0x3e0293ee, v122
	s_waitcnt lgkmcnt(0)
	v_mfma_f32_16x16x32_bf16 v[96:99], v[96:99], v[0:3], 0
	v_mul_f32_e32 v123, 0x3e0293ee, v123
	v_mfma_f32_16x16x32_bf16 v[96:99], v[124:127], v[4:7], v[96:99]
	ds_read_b128 v[124:127], v136 offset:4480
	s_waitcnt lgkmcnt(0)
	v_mfma_f32_16x16x32_bf16 v[96:99], v[124:127], v[8:11], v[96:99]
	ds_read_b128 v[124:127], v136 offset:4544
	s_waitcnt lgkmcnt(0)
	v_mfma_f32_16x16x32_bf16 v[124:127], v[124:127], v[12:15], v[96:99]
	s_nop 4
	ds_read_b128 v[96:99], v136 offset:8704
	s_nop 1
	v_mul_f32_e32 v124, 0x3e0293ee, v124
	s_waitcnt lgkmcnt(0)
	v_mfma_f32_16x16x32_bf16 v[96:99], v[96:99], v[0:3], 0
	v_mul_f32_e32 v125, 0x3e0293ee, v125
	v_mul_f32_e32 v126, 0x3e0293ee, v126
	v_mul_f32_e32 v127, 0x3e0293ee, v127
	v_mfma_f32_16x16x32_bf16 v[96:99], v[128:131], v[4:7], v[96:99]
	ds_read_b128 v[128:131], v136 offset:8832
	s_waitcnt lgkmcnt(0)
	v_mfma_f32_16x16x32_bf16 v[96:99], v[128:131], v[8:11], v[96:99]
	ds_read_b128 v[128:131], v136 offset:8896
	s_waitcnt lgkmcnt(0)
	v_mfma_f32_16x16x32_bf16 v[128:131], v[128:131], v[12:15], v[96:99]
	s_nop 4
	ds_read_b128 v[96:99], v136 offset:13056
	s_nop 1
	v_mul_f32_e32 v128, 0x3e0293ee, v128
	s_waitcnt lgkmcnt(0)
	v_mfma_f32_16x16x32_bf16 v[96:99], v[96:99], v[0:3], 0
	v_mul_f32_e32 v129, 0x3e0293ee, v129
	v_mul_f32_e32 v130, 0x3e0293ee, v130
	v_mul_f32_e32 v131, 0x3e0293ee, v131
	v_mfma_f32_16x16x32_bf16 v[96:99], v[132:135], v[4:7], v[96:99]
	ds_read_b128 v[132:135], v136 offset:13184
	s_waitcnt lgkmcnt(0)
	v_mfma_f32_16x16x32_bf16 v[96:99], v[132:135], v[8:11], v[96:99]
	ds_read_b128 v[132:135], v136 offset:13248
	s_waitcnt lgkmcnt(0)
	v_mfma_f32_16x16x32_bf16 v[96:99], v[132:135], v[12:15], v[96:99]
	s_nop 3
	v_add_u32_e32 v133, 2, v119
	s_nop 2
	v_mul_f32_e32 v96, 0x3e0293ee, v96
	v_cndmask_b32_e32 v120, v238, v120, vcc
	v_cmp_lt_i32_e32 vcc, v119, v200
	v_mul_f32_e32 v97, 0x3e0293ee, v97
	v_mul_f32_e32 v98, 0x3e0293ee, v98
	s_nop 3
	v_mul_f32_e32 v99, 0x3e0293ee, v99
	s_nop 0
	v_cndmask_b32_e32 v121, v238, v121, vcc
	v_cmp_le_i32_e32 vcc, v133, v200
	v_max3_f32 v132, v117, v120, v121
	s_nop 0
	v_add_u32_e32 v133, 3, v119
	s_nop 0
	v_cndmask_b32_e32 v122, v238, v122, vcc
	v_cmp_le_i32_e32 vcc, v133, v200
	s_nop 1
	v_add_u32_e32 v133, 4, v119
	s_nop 0
	v_cndmask_b32_e32 v123, v238, v123, vcc
	v_cmp_le_i32_e32 vcc, v133, v200
	v_max3_f32 v132, v132, v122, v123
	s_nop 0
	v_add_u32_e32 v133, 5, v119
	s_nop 0
	v_cndmask_b32_e32 v124, v238, v124, vcc
	v_cmp_le_i32_e32 vcc, v133, v200
	s_nop 1
	v_add_u32_e32 v133, 6, v119
	s_nop 0
	v_cndmask_b32_e32 v125, v238, v125, vcc
	v_cmp_le_i32_e32 vcc, v133, v200
	v_max3_f32 v132, v132, v124, v125
	s_nop 0
	v_add_u32_e32 v133, 7, v119
	s_nop 0
	v_cndmask_b32_e32 v126, v238, v126, vcc
	v_cmp_le_i32_e32 vcc, v133, v200
	s_nop 1
	v_add_u32_e32 v133, 32, v119
	s_nop 0
	v_cndmask_b32_e32 v127, v238, v127, vcc
	v_cmp_le_i32_e32 vcc, v133, v200
	v_max3_f32 v132, v132, v126, v127
	s_nop 0
	v_add_u32_e32 v133, 33, v119
	s_nop 0
	v_cndmask_b32_e32 v128, v238, v128, vcc
	v_cmp_le_i32_e32 vcc, v133, v200
	s_nop 1
	v_add_u32_e32 v133, 34, v119
	s_nop 0
	v_cndmask_b32_e32 v129, v238, v129, vcc
	v_cmp_le_i32_e32 vcc, v133, v200
	v_max3_f32 v132, v132, v128, v129
	s_nop 0
	v_add_u32_e32 v133, 35, v119
	s_nop 0
	v_cndmask_b32_e32 v130, v238, v130, vcc
	v_cmp_le_i32_e32 vcc, v133, v200
	s_nop 1
	v_add_u32_e32 v133, 36, v119
	s_nop 0
	v_cndmask_b32_e32 v131, v238, v131, vcc
	v_cmp_le_i32_e32 vcc, v133, v200
	v_max3_f32 v132, v132, v130, v131
	s_nop 0
	v_add_u32_e32 v133, 37, v119
	s_nop 0
	v_cndmask_b32_e32 v96, v238, v96, vcc
	v_cmp_le_i32_e32 vcc, v133, v200
	s_nop 1
	s_nop 1
	v_cndmask_b32_e32 v133, v238, v97, vcc
	v_max3_f32 v97, v132, v96, v133
	v_add_u32_e32 v132, 38, v119
	v_cmp_le_i32_e32 vcc, v132, v200
	v_add_u32_e32 v119, 39, v119
	s_nop 0
	s_nop 1
	v_cndmask_b32_e32 v98, v238, v98, vcc
	v_cmp_le_i32_e32 vcc, v119, v200
	s_nop 1
	v_and_b32_e32 v119, 64, v239
	v_xor_b32_e32 v118, 16, v239
	v_add_u32_e32 v119, 64, v119
	v_cndmask_b32_e32 v99, v238, v99, vcc
	v_cmp_lt_i32_e32 vcc, v118, v119
	v_max3_f32 v97, v97, v98, v99
	s_nop 0
	v_cndmask_b32_e32 v118, v239, v118, vcc
	v_lshlrev_b32_e32 v118, 2, v118
	ds_bpermute_b32 v118, v118, v97
	s_waitcnt lgkmcnt(0)
	v_max_f32_e32 v118, v118, v118
	v_max_f32_e32 v97, v97, v118
	v_xor_b32_e32 v118, 32, v239
	v_cmp_lt_i32_e32 vcc, v118, v119
	s_nop 1
	v_cndmask_b32_e32 v118, v239, v118, vcc
	v_lshlrev_b32_e32 v118, 2, v118
	ds_bpermute_b32 v118, v118, v97
	s_waitcnt lgkmcnt(0)
	v_max_f32_e32 v118, v118, v118
	v_max_f32_e32 v97, v97, v118
	v_sub_f32_e32 v118, v120, v97
	v_exp_f32_e32 v134, v118
	v_sub_f32_e32 v119, v121, v97
	v_exp_f32_e32 v135, v119
	v_sub_f32_e32 v119, v122, v97
	v_exp_f32_e32 v136, v119
	v_sub_f32_e32 v119, v123, v97
	v_exp_f32_e32 v137, v119
	v_sub_f32_e32 v119, v124, v97
	v_add_f32_e32 v118, 0, v134
	v_exp_f32_e32 v138, v119
	v_sub_f32_e32 v119, v125, v97
	v_add_f32_e32 v118, v135, v118
	v_exp_f32_e32 v139, v119
	v_sub_f32_e32 v119, v126, v97
	v_add_f32_e32 v118, v136, v118
	v_exp_f32_e32 v140, v119
	v_sub_f32_e32 v119, v127, v97
	v_add_f32_e32 v118, v137, v118
	v_exp_f32_e32 v141, v119
	v_sub_f32_e32 v119, v128, v97
	v_add_f32_e32 v118, v138, v118
	v_exp_f32_e32 v142, v119
	v_sub_f32_e32 v119, v129, v97
	v_sub_f32_e32 v96, v96, v97
	v_add_f32_e32 v118, v139, v118
	v_exp_f32_e32 v143, v119
	v_sub_f32_e32 v119, v130, v97
	v_exp_f32_e32 v147, v96
	v_sub_f32_e32 v96, v133, v97
	v_add_f32_e32 v118, v140, v118
	v_exp_f32_e32 v144, v119
	v_sub_f32_e32 v119, v131, v97
	v_exp_f32_e32 v148, v96
	v_sub_f32_e32 v96, v98, v97
	v_sub_f32_e32 v117, v117, v97
	v_add_f32_e32 v118, v141, v118
	v_exp_f32_e32 v145, v119
	v_exp_f32_e32 v149, v96
	v_sub_f32_e32 v96, v99, v97
	v_add_f32_e32 v118, v142, v118
	v_exp_f32_e32 v99, v96
	v_exp_f32_e32 v96, v117
	v_add_f32_e32 v118, v143, v118
	v_add_f32_e32 v118, v144, v118
	v_add_f32_e32 v146, v145, v118
	v_pk_mul_f32 v[130:131], v[76:77], v[96:97] op_sel_hi:[1,0]
	v_pk_mul_f32 v[76:77], v[80:81], v[96:97] op_sel_hi:[1,0]
	v_add_f32_e32 v80, v147, v146
	v_add_f32_e32 v80, v148, v80
	v_add_f32_e32 v80, v149, v80
	v_add3_u32 v117, v114, s8, v116
	v_pk_mul_f32 v[124:125], v[70:71], v[96:97] op_sel_hi:[1,0]
	v_pk_mul_f32 v[122:123], v[68:69], v[96:97] op_sel_hi:[1,0]
	v_pk_mul_f32 v[128:129], v[74:75], v[96:97] op_sel_hi:[1,0]
	v_pk_mul_f32 v[126:127], v[72:73], v[96:97] op_sel_hi:[1,0]
	v_pk_mul_f32 v[132:133], v[78:79], v[96:97] op_sel_hi:[1,0]
	v_pk_mul_f32 v[78:79], v[82:83], v[96:97] op_sel_hi:[1,0]
	v_pk_mul_f32 v[74:75], v[86:87], v[96:97] op_sel_hi:[1,0]
	v_pk_mul_f32 v[72:73], v[84:85], v[96:97] op_sel_hi:[1,0]
	v_pk_mul_f32 v[70:71], v[90:91], v[96:97] op_sel_hi:[1,0]
	v_pk_mul_f32 v[68:69], v[88:89], v[96:97] op_sel_hi:[1,0]
	v_add_f32_e32 v98, v99, v80
	v_cvt_pk_bf16_f32 v80, v134, v135
	v_cvt_pk_bf16_f32 v81, v136, v137
	v_cvt_pk_bf16_f32 v82, v138, v139
	v_cvt_pk_bf16_f32 v83, v140, v141
	ds_read_b128 v[84:87], v117 offset:34816
	ds_read_b128 v[88:91], v117 offset:37120
	s_waitcnt lgkmcnt(0)
	v_mfma_f32_16x16x32_bf16 v[88:91], v[88:91], v[80:83], v[122:125]
	s_nop 2
	ds_read_b128 v[122:125], v117 offset:44032
	v_pk_mul_f32 v[120:121], v[66:67], v[96:97] op_sel_hi:[1,0]
	v_pk_mul_f32 v[118:119], v[64:65], v[96:97] op_sel_hi:[1,0]
	v_pk_mul_f32 v[66:67], v[94:95], v[96:97] op_sel_hi:[1,0]
	v_pk_mul_f32 v[64:65], v[92:93], v[96:97] op_sel_hi:[1,0]
	ds_read_b128 v[92:95], v117 offset:39424
	s_waitcnt lgkmcnt(1)
	v_mfma_f32_16x16x32_bf16 v[122:125], v[122:125], v[80:83], v[76:79]
	s_nop 2
	ds_read_b128 v[76:79], v117 offset:46336
	v_fmac_f32_e32 v98, v112, v96
	v_mov_b32_e32 v112, v98
	v_mfma_f32_16x16x32_bf16 v[84:87], v[84:87], v[80:83], v[118:121]
	s_nop 2
	ds_read_b128 v[118:121], v117 offset:41728
	s_waitcnt lgkmcnt(2)
	v_mfma_f32_16x16x32_bf16 v[92:95], v[92:95], v[80:83], v[126:129]
	s_waitcnt lgkmcnt(1)
	v_mfma_f32_16x16x32_bf16 v[126:129], v[76:79], v[80:83], v[72:75]
	s_nop 2
	ds_read_b128 v[72:75], v117 offset:48640
	s_waitcnt lgkmcnt(1)
	v_mfma_f32_16x16x32_bf16 v[118:121], v[118:121], v[80:83], v[130:133]
	s_waitcnt lgkmcnt(0)
	v_mfma_f32_16x16x32_bf16 v[130:133], v[72:75], v[80:83], v[68:71]
	s_nop 2
	ds_read_b128 v[68:71], v117 offset:50944
	v_cvt_pk_bf16_f32 v138, v142, v143
	v_cvt_pk_bf16_f32 v139, v144, v145
	s_waitcnt lgkmcnt(0)
	v_mfma_f32_16x16x32_bf16 v[134:137], v[68:71], v[80:83], v[64:67]
	v_cvt_pk_bf16_f32 v140, v147, v148
	v_cvt_pk_bf16_f32 v141, v149, v99
	s_nop 2
	ds_read_b128 v[64:67], v117 offset:34880
	ds_read_b128 v[68:71], v117 offset:37184
	ds_read_b128 v[72:75], v117 offset:39488
	ds_read_b128 v[76:79], v117 offset:41792
	s_waitcnt lgkmcnt(3)
	v_mfma_f32_16x16x32_bf16 v[64:67], v[64:67], v[138:141], v[84:87]
	ds_read_b128 v[80:83], v117 offset:44096
	s_nop 1
	ds_read_b128 v[84:87], v117 offset:46400
	s_waitcnt lgkmcnt(4)
	v_mfma_f32_16x16x32_bf16 v[68:71], v[68:71], v[138:141], v[88:91]
	s_waitcnt lgkmcnt(3)
	v_mfma_f32_16x16x32_bf16 v[72:75], v[72:75], v[138:141], v[92:95]
	s_nop 0
	ds_read_b128 v[88:91], v117 offset:48704
	s_nop 0
	ds_read_b128 v[92:95], v117 offset:51008
	s_waitcnt lgkmcnt(4)
	v_mfma_f32_16x16x32_bf16 v[76:79], v[76:79], v[138:141], v[118:121]
	v_mov_b32_e32 v117, v97
	s_waitcnt lgkmcnt(3)
	v_mfma_f32_16x16x32_bf16 v[80:83], v[80:83], v[138:141], v[122:125]
	s_waitcnt lgkmcnt(2)
	v_mfma_f32_16x16x32_bf16 v[84:87], v[84:87], v[138:141], v[126:129]
	s_waitcnt lgkmcnt(1)
	v_mfma_f32_16x16x32_bf16 v[88:91], v[88:91], v[138:141], v[130:133]
	s_waitcnt lgkmcnt(0)
	v_mfma_f32_16x16x32_bf16 v[92:95], v[92:95], v[138:141], v[134:137]

.LBB0_290:
	v_add3_u32 v136, s56, v102, v115
	ds_read_b128 v[96:99], v136
	ds_read_b128 v[120:123], v136 offset:64
	v_and_b32_e32 v201, 1, v118
	v_mov_b32_e32 v200, 0x80000000
	v_cmp_eq_u32_e32 vcc, 1, v201
	v_mov_b32_e32 v201, 0x7fffffff
	s_nop 0
	v_cndmask_b32_e32 v200, v200, v201, vcc
	v_cndmask_b32_e64 v200, v100, v200, s[0:1]
	v_add_u32_e32 v119, v119, v104
	v_cmp_le_i32_e32 vcc, v119, v200
	s_waitcnt lgkmcnt(1)
	v_mfma_f32_16x16x32_bf16 v[96:99], v[96:99], v[0:3], 0
	ds_read_b128 v[124:127], v136 offset:4416
	ds_read_b128 v[128:131], v136 offset:8768
	ds_read_b128 v[132:135], v136 offset:13120
	s_waitcnt lgkmcnt(3)
	v_mfma_f32_16x16x32_bf16 v[96:99], v[120:123], v[4:7], v[96:99]
	ds_read_b128 v[120:123], v136 offset:128
	s_waitcnt lgkmcnt(0)
	v_mfma_f32_16x16x32_bf16 v[96:99], v[120:123], v[8:11], v[96:99]
	ds_read_b128 v[120:123], v136 offset:192
	s_waitcnt lgkmcnt(0)
	v_mfma_f32_16x16x32_bf16 v[120:123], v[120:123], v[12:15], v[96:99]
	s_nop 4
	ds_read_b128 v[96:99], v136 offset:4352
	s_nop 1
	v_mul_f32_e32 v120, 0x3e0293ee, v120
	v_mul_f32_e32 v121, 0x3e0293ee, v121
	v_mul_f32_e32 v122, 0x3e0293ee, v122
	s_waitcnt lgkmcnt(0)
	v_mfma_f32_16x16x32_bf16 v[96:99], v[96:99], v[0:3], 0
	v_mul_f32_e32 v123, 0x3e0293ee, v123
	v_mfma_f32_16x16x32_bf16 v[96:99], v[124:127], v[4:7], v[96:99]
	ds_read_b128 v[124:127], v136 offset:4480
	s_waitcnt lgkmcnt(0)
	v_mfma_f32_16x16x32_bf16 v[96:99], v[124:127], v[8:11], v[96:99]
	ds_read_b128 v[124:127], v136 offset:4544
	s_waitcnt lgkmcnt(0)
	v_mfma_f32_16x16x32_bf16 v[124:127], v[124:127], v[12:15], v[96:99]
	s_nop 4
	ds_read_b128 v[96:99], v136 offset:8704
	s_nop 1
	v_mul_f32_e32 v124, 0x3e0293ee, v124
	s_waitcnt lgkmcnt(0)
	v_mfma_f32_16x16x32_bf16 v[96:99], v[96:99], v[0:3], 0
	v_mul_f32_e32 v125, 0x3e0293ee, v125
	v_mul_f32_e32 v126, 0x3e0293ee, v126
	v_mul_f32_e32 v127, 0x3e0293ee, v127
	v_mfma_f32_16x16x32_bf16 v[96:99], v[128:131], v[4:7], v[96:99]
	ds_read_b128 v[128:131], v136 offset:8832
	s_waitcnt lgkmcnt(0)
	v_mfma_f32_16x16x32_bf16 v[96:99], v[128:131], v[8:11], v[96:99]
	ds_read_b128 v[128:131], v136 offset:8896
	s_waitcnt lgkmcnt(0)
	v_mfma_f32_16x16x32_bf16 v[128:131], v[128:131], v[12:15], v[96:99]
	s_nop 4
	ds_read_b128 v[96:99], v136 offset:13056
	s_nop 1
	v_mul_f32_e32 v128, 0x3e0293ee, v128
	s_waitcnt lgkmcnt(0)
	v_mfma_f32_16x16x32_bf16 v[96:99], v[96:99], v[0:3], 0
	v_mul_f32_e32 v129, 0x3e0293ee, v129
	v_mul_f32_e32 v130, 0x3e0293ee, v130
	v_mul_f32_e32 v131, 0x3e0293ee, v131
	v_mfma_f32_16x16x32_bf16 v[96:99], v[132:135], v[4:7], v[96:99]
	ds_read_b128 v[132:135], v136 offset:13184
	s_waitcnt lgkmcnt(0)
	v_mfma_f32_16x16x32_bf16 v[96:99], v[132:135], v[8:11], v[96:99]
	ds_read_b128 v[132:135], v136 offset:13248
	s_waitcnt lgkmcnt(0)
	v_mfma_f32_16x16x32_bf16 v[96:99], v[132:135], v[12:15], v[96:99]
	s_nop 3
	v_add_u32_e32 v133, 2, v119
	s_nop 2
	v_mul_f32_e32 v96, 0x3e0293ee, v96
	v_cndmask_b32_e32 v120, v238, v120, vcc
	v_cmp_lt_i32_e32 vcc, v119, v200
	v_mul_f32_e32 v97, 0x3e0293ee, v97
	v_mul_f32_e32 v98, 0x3e0293ee, v98
	s_nop 3
	v_mul_f32_e32 v99, 0x3e0293ee, v99
	s_nop 0
	v_cndmask_b32_e32 v121, v238, v121, vcc
	v_cmp_le_i32_e32 vcc, v133, v200
	v_max3_f32 v132, v117, v120, v121
	s_nop 0
	v_add_u32_e32 v133, 3, v119
	s_nop 0
	v_cndmask_b32_e32 v122, v238, v122, vcc
	v_cmp_le_i32_e32 vcc, v133, v200
	s_nop 1
	v_add_u32_e32 v133, 4, v119
	s_nop 0
	v_cndmask_b32_e32 v123, v238, v123, vcc
	v_cmp_le_i32_e32 vcc, v133, v200
	v_max3_f32 v132, v132, v122, v123
	s_nop 0
	v_add_u32_e32 v133, 5, v119
	s_nop 0
	v_cndmask_b32_e32 v124, v238, v124, vcc
	v_cmp_le_i32_e32 vcc, v133, v200
	s_nop 1
	v_add_u32_e32 v133, 6, v119
	s_nop 0
	v_cndmask_b32_e32 v125, v238, v125, vcc
	v_cmp_le_i32_e32 vcc, v133, v200
	v_max3_f32 v132, v132, v124, v125
	s_nop 0
	v_add_u32_e32 v133, 7, v119
	s_nop 0
	v_cndmask_b32_e32 v126, v238, v126, vcc
	v_cmp_le_i32_e32 vcc, v133, v200
	s_nop 1
	v_add_u32_e32 v133, 32, v119
	s_nop 0
	v_cndmask_b32_e32 v127, v238, v127, vcc
	v_cmp_le_i32_e32 vcc, v133, v200
	v_max3_f32 v132, v132, v126, v127
	s_nop 0
	v_add_u32_e32 v133, 33, v119
	s_nop 0
	v_cndmask_b32_e32 v128, v238, v128, vcc
	v_cmp_le_i32_e32 vcc, v133, v200
	s_nop 1
	v_add_u32_e32 v133, 34, v119
	s_nop 0
	v_cndmask_b32_e32 v129, v238, v129, vcc
	v_cmp_le_i32_e32 vcc, v133, v200
	v_max3_f32 v132, v132, v128, v129
	s_nop 0
	v_add_u32_e32 v133, 35, v119
	s_nop 0
	v_cndmask_b32_e32 v130, v238, v130, vcc
	v_cmp_le_i32_e32 vcc, v133, v200
	s_nop 1
	v_add_u32_e32 v133, 36, v119
	s_nop 0
	v_cndmask_b32_e32 v131, v238, v131, vcc
	v_cmp_le_i32_e32 vcc, v133, v200
	v_max3_f32 v132, v132, v130, v131
	s_nop 0
	v_add_u32_e32 v133, 37, v119
	s_nop 0
	v_cndmask_b32_e32 v96, v238, v96, vcc
	v_cmp_le_i32_e32 vcc, v133, v200
	s_nop 1
	s_nop 1
	v_cndmask_b32_e32 v133, v238, v97, vcc
	v_max3_f32 v97, v132, v96, v133
	v_add_u32_e32 v132, 38, v119
	v_cmp_le_i32_e32 vcc, v132, v200
	v_add_u32_e32 v119, 39, v119
	s_nop 0
	s_nop 1
	v_cndmask_b32_e32 v98, v238, v98, vcc
	v_cmp_le_i32_e32 vcc, v119, v200
	s_nop 1
	v_and_b32_e32 v119, 64, v239
	v_xor_b32_e32 v118, 16, v239
	v_add_u32_e32 v119, 64, v119
	v_cndmask_b32_e32 v99, v238, v99, vcc
	v_cmp_lt_i32_e32 vcc, v118, v119
	v_max3_f32 v97, v97, v98, v99
	s_nop 0
	v_cndmask_b32_e32 v118, v239, v118, vcc
	v_lshlrev_b32_e32 v118, 2, v118
	ds_bpermute_b32 v118, v118, v97
	s_waitcnt lgkmcnt(0)
; __device__ __forceinline__ void attn_item(const Params& p, int item, unsigned char* smem) {
;     ...
; #pragma unroll 1
;     for (int it = 0; it < ntiles; it += 3) {
;         ATT_BODY(it, s1);
;         if (it + 1 >= ntiles) break;
;         ATT_BODY(it + 1, s2);
;         if (it + 2 >= ntiles) break;
;         ATT_BODY(it + 2, s0);
;     }
	v_max_f32_e32 v118, v118, v118
	v_max_f32_e32 v97, v97, v118
	v_xor_b32_e32 v118, 32, v239
	v_cmp_lt_i32_e32 vcc, v118, v119
	s_nop 1
	v_cndmask_b32_e32 v118, v239, v118, vcc
	v_lshlrev_b32_e32 v118, 2, v118
	ds_bpermute_b32 v118, v118, v97
	s_waitcnt lgkmcnt(0)
	v_max_f32_e32 v118, v118, v118
	v_max_f32_e32 v97, v97, v118
	v_sub_f32_e32 v118, v120, v97
	v_exp_f32_e32 v134, v118
	v_sub_f32_e32 v119, v121, v97
	v_exp_f32_e32 v135, v119
	v_sub_f32_e32 v119, v122, v97
	v_exp_f32_e32 v136, v119
	v_sub_f32_e32 v119, v123, v97
	v_exp_f32_e32 v137, v119
	v_sub_f32_e32 v119, v124, v97
	v_add_f32_e32 v118, 0, v134
	v_exp_f32_e32 v138, v119
	v_sub_f32_e32 v119, v125, v97
	v_add_f32_e32 v118, v135, v118
	v_exp_f32_e32 v139, v119
	v_sub_f32_e32 v119, v126, v97
	v_add_f32_e32 v118, v136, v118
	v_exp_f32_e32 v140, v119
	v_sub_f32_e32 v119, v127, v97
	v_add_f32_e32 v118, v137, v118
	v_exp_f32_e32 v141, v119
	v_sub_f32_e32 v119, v128, v97
	v_add_f32_e32 v118, v138, v118
	v_exp_f32_e32 v142, v119
	v_sub_f32_e32 v119, v129, v97
	v_sub_f32_e32 v96, v96, v97
	v_add_f32_e32 v118, v139, v118
	v_exp_f32_e32 v143, v119
	v_sub_f32_e32 v119, v130, v97
	v_exp_f32_e32 v147, v96
	v_sub_f32_e32 v96, v133, v97
	v_add_f32_e32 v118, v140, v118
	v_exp_f32_e32 v144, v119
	v_sub_f32_e32 v119, v131, v97
	v_exp_f32_e32 v148, v96
	v_sub_f32_e32 v96, v98, v97
	v_sub_f32_e32 v117, v117, v97
	v_add_f32_e32 v118, v141, v118
	v_exp_f32_e32 v145, v119
	v_exp_f32_e32 v149, v96
	v_sub_f32_e32 v96, v99, v97
	v_add_f32_e32 v118, v142, v118
	v_exp_f32_e32 v99, v96
	v_exp_f32_e32 v96, v117
	v_add_f32_e32 v118, v143, v118
	v_add_f32_e32 v118, v144, v118
	v_add_f32_e32 v146, v145, v118
	v_pk_mul_f32 v[130:131], v[76:77], v[96:97] op_sel_hi:[1,0]
	v_pk_mul_f32 v[76:77], v[80:81], v[96:97] op_sel_hi:[1,0]
	v_add_f32_e32 v80, v147, v146
	v_add_f32_e32 v80, v148, v80
	v_add_f32_e32 v80, v149, v80
	v_add3_u32 v117, s55, v102, v116
	v_pk_mul_f32 v[124:125], v[70:71], v[96:97] op_sel_hi:[1,0]
	v_pk_mul_f32 v[122:123], v[68:69], v[96:97] op_sel_hi:[1,0]
	v_pk_mul_f32 v[128:129], v[74:75], v[96:97] op_sel_hi:[1,0]
	v_pk_mul_f32 v[126:127], v[72:73], v[96:97] op_sel_hi:[1,0]
	v_pk_mul_f32 v[132:133], v[78:79], v[96:97] op_sel_hi:[1,0]
	v_pk_mul_f32 v[78:79], v[82:83], v[96:97] op_sel_hi:[1,0]
	v_pk_mul_f32 v[74:75], v[86:87], v[96:97] op_sel_hi:[1,0]
	v_pk_mul_f32 v[72:73], v[84:85], v[96:97] op_sel_hi:[1,0]
	v_pk_mul_f32 v[70:71], v[90:91], v[96:97] op_sel_hi:[1,0]
	v_pk_mul_f32 v[68:69], v[88:89], v[96:97] op_sel_hi:[1,0]
	v_add_f32_e32 v98, v99, v80
	v_cvt_pk_bf16_f32 v80, v134, v135
	v_cvt_pk_bf16_f32 v81, v136, v137
	v_cvt_pk_bf16_f32 v82, v138, v139
	v_cvt_pk_bf16_f32 v83, v140, v141
	ds_read_b128 v[84:87], v117 offset:34816
	ds_read_b128 v[88:91], v117 offset:37120
	s_waitcnt lgkmcnt(0)
	v_mfma_f32_16x16x32_bf16 v[88:91], v[88:91], v[80:83], v[122:125]
	s_nop 2
	ds_read_b128 v[122:125], v117 offset:44032
	v_pk_mul_f32 v[120:121], v[66:67], v[96:97] op_sel_hi:[1,0]
	v_pk_mul_f32 v[118:119], v[64:65], v[96:97] op_sel_hi:[1,0]
	v_pk_mul_f32 v[66:67], v[94:95], v[96:97] op_sel_hi:[1,0]
	v_pk_mul_f32 v[64:65], v[92:93], v[96:97] op_sel_hi:[1,0]
	ds_read_b128 v[92:95], v117 offset:39424
	s_waitcnt lgkmcnt(1)
	v_mfma_f32_16x16x32_bf16 v[122:125], v[122:125], v[80:83], v[76:79]
	s_nop 2
	ds_read_b128 v[76:79], v117 offset:46336
	v_fmac_f32_e32 v98, v112, v96
	v_mov_b32_e32 v112, v98
	v_mfma_f32_16x16x32_bf16 v[84:87], v[84:87], v[80:83], v[118:121]
	s_nop 2
	ds_read_b128 v[118:121], v117 offset:41728
	s_waitcnt lgkmcnt(2)
	v_mfma_f32_16x16x32_bf16 v[92:95], v[92:95], v[80:83], v[126:129]
	s_waitcnt lgkmcnt(1)
	v_mfma_f32_16x16x32_bf16 v[126:129], v[76:79], v[80:83], v[72:75]
	s_nop 2
	ds_read_b128 v[72:75], v117 offset:48640
	s_waitcnt lgkmcnt(1)
	v_mfma_f32_16x16x32_bf16 v[118:121], v[118:121], v[80:83], v[130:133]
	s_waitcnt lgkmcnt(0)
	v_mfma_f32_16x16x32_bf16 v[130:133], v[72:75], v[80:83], v[68:71]
	s_nop 2
	ds_read_b128 v[68:71], v117 offset:50944
	v_cvt_pk_bf16_f32 v138, v142, v143
	v_cvt_pk_bf16_f32 v139, v144, v145
	s_waitcnt lgkmcnt(0)
	v_mfma_f32_16x16x32_bf16 v[134:137], v[68:71], v[80:83], v[64:67]
	v_cvt_pk_bf16_f32 v140, v147, v148
	v_cvt_pk_bf16_f32 v141, v149, v99
	s_nop 2
	ds_read_b128 v[64:67], v117 offset:34880
	ds_read_b128 v[68:71], v117 offset:37184
	ds_read_b128 v[72:75], v117 offset:39488
	ds_read_b128 v[76:79], v117 offset:41792
	s_waitcnt lgkmcnt(3)
	v_mfma_f32_16x16x32_bf16 v[64:67], v[64:67], v[138:141], v[84:87]
	ds_read_b128 v[80:83], v117 offset:44096
	s_nop 1
	ds_read_b128 v[84:87], v117 offset:46400
	s_waitcnt lgkmcnt(4)
	v_mfma_f32_16x16x32_bf16 v[68:71], v[68:71], v[138:141], v[88:91]
	s_waitcnt lgkmcnt(3)
	v_mfma_f32_16x16x32_bf16 v[72:75], v[72:75], v[138:141], v[92:95]
	s_nop 0
	ds_read_b128 v[88:91], v117 offset:48704
	s_nop 0
	ds_read_b128 v[92:95], v117 offset:51008
	s_waitcnt lgkmcnt(4)
	v_mfma_f32_16x16x32_bf16 v[76:79], v[76:79], v[138:141], v[118:121]
	v_mov_b32_e32 v117, v97
	s_waitcnt lgkmcnt(3)
	v_mfma_f32_16x16x32_bf16 v[80:83], v[80:83], v[138:141], v[122:125]
	s_waitcnt lgkmcnt(2)
	v_mfma_f32_16x16x32_bf16 v[84:87], v[84:87], v[138:141], v[126:129]
	s_waitcnt lgkmcnt(1)
	v_mfma_f32_16x16x32_bf16 v[88:91], v[88:91], v[138:141], v[130:133]
	s_waitcnt lgkmcnt(0)
	v_mfma_f32_16x16x32_bf16 v[92:95], v[92:95], v[138:141], v[134:137]
	s_or_b64 exec, exec, s[40:41]
	s_add_i32 s0, s46, -3
	s_cmp_ge_i32 s0, s2
	s_cbranch_scc0 .LBB0_299

; __device__ __forceinline__ int opaque_tid() { int t = threadIdx.x; asm volatile("" : "+v"(t)); return t; }
; #define CVT_LOAD(tile_) do { const int k0_ = ((tile_) / ntn) << 7, n0_ = ((tile_) % ntn) << 6; \
;         _Pragma("unroll") for (int pp = 0; pp < 4; ++pp) pv[pp] = *(const float4*)(src + (size_t)(k0_ + lk + 32 * pp) * N + n0_ + ln4); } while (0)
; __device__ __forceinline__ void convT_job(const float* __restrict__ src, bf16_t* __restrict__ dst, int K, int N, int mode, float* t) {
;     const int tid = opaque_tid(), ntn = N >> 6, ntiles = (K >> 7) * ntn;
;     const int lk = tid >> 4, ln4 = (tid & 15) * 4;
;     float4 pv[4];
;     ...
;     int tile = blockIdx.x;
;     if (tile < ntiles) CVT_LOAD(tile);
; #pragma unroll 1
;     for (; tile < ntiles; tile += gridDim.x) {
;         const int k0 = (tile / ntn) << 7, n0 = (tile % ntn) << 6;
; #pragma unroll
;         for (int pp = 0; pp < 4; ++pp) { const int k = lk + 32 * pp; t[k * 65 + ln4] = pv[pp].x; t[k * 65 + ln4 + 1] = pv[pp].y; t[k * 65 + ln4 + 2] = pv[pp].z; t[k * 65 + ln4 + 3] = pv[pp].w; }
;         if (tile + (int)gridDim.x < ntiles) CVT_LOAD(tile + (int)gridDim.x);
; __device__ __forceinline__ void phase_convert(const Params& p, unsigned char* smem) {
;     ...
;             convT_job(p.in[3] + wo, gu, 2048, 5632, 1, t);
.LBB0_623:
	s_load_dword s98, s[96:97], 0x0
	v_lshrrev_b32_e32 v6, 6, v234
	v_and_b32_e32 v25, 63, v234
	v_lshrrev_b32_e32 v26, 3, v234
	v_readfirstlane_b32 s46, v6
	v_and_b32_e32 v27, 7, v234
	v_readlane_b32 s54, v255, 28
	v_readlane_b32 s55, v255, 29
	s_lshl_b32 s46, s46, 12
	v_lshrrev_b32_e32 v28, 2, v26
	v_xor_b32_e32 v28, v28, v27
	v_lshlrev_b32_e32 v28, 4, v28
	v_and_b32_e32 v29, 3, v26
	v_lshl_or_b32 v28, v29, 2, v28
	v_lshl_or_b32 v4, v27, 12, v28
	v_lshrrev_b32_e32 v30, 4, v25
	v_lshl_add_u32 v30, v6, 4, v30
	v_and_b32_e32 v31, 15, v25
	v_xor_b32_e32 v31, v31, v6
	v_lshlrev_b32_e32 v31, 4, v31
	v_lshlrev_b32_e32 v27, 5, v27
	s_waitcnt lgkmcnt(0)
	s_mov_b32 s40, s60
	s_cmp_lt_u32 s40, 1408
	s_cbranch_scc0 .Lcv_gate_skip
	v_mov_b32_e32 v29, 0x5800
	v_mov_b32_e32 v28, 0x1000
	v_mad_u32_u24 v0, v30, v29, v31
	v_mad_u32_u24 v5, v26, v28, v27
	v_add_u32_e32 v1, 0x16000, v0
	v_add_u32_e32 v2, 0x2c000, v0
	v_add_u32_e32 v3, 0x42000, v0
	s_barrier
	s_mov_b32 s41, 0
	s_mov_b32 s47, s40
	s_mov_b32 s48, s46
	s_mul_hi_u32 s0, s47, 0x2e8ba3
	s_mul_i32 s1, s0, 1408
	s_sub_u32 s1, s47, s1
	s_mul_hi_u32 s2, s1, 0x2e8ba2f
	s_mul_i32 s8, s2, 88
	s_sub_u32 s8, s1, s8
	s_mul_i32 s9, s0, 0x2c00000
	s_mul_i32 s28, s2, 0x2c0000
	s_add_u32 s9, s9, s28
	s_lshl_b32 s8, s8, 8
	s_add_u32 s9, s9, s8
	s_add_u32 s42, s70, s9
	s_addc_u32 s43, s71, 0
	s_mov_b32 m0, s48
	s_add_u32 s49, s48, 0x400
	global_load_lds_dwordx4 v0, s[42:43] nt
	s_mov_b32 m0, s49
	s_add_u32 s49, s48, 0x800
	global_load_lds_dwordx4 v1, s[42:43] nt
	s_mov_b32 m0, s49
	s_add_u32 s49, s48, 0xc00
	global_load_lds_dwordx4 v2, s[42:43] nt
	s_mov_b32 m0, s49
	s_nop 0
	global_load_lds_dwordx4 v3, s[42:43] nt
	global_load_dword v24, v173, s[70:71]
	global_load_dword v24, v173, s[70:71]
	s_add_u32 s47, s40, s98
	s_add_u32 s48, s46, 0x8000
	s_cmp_lt_u32 s47, 1408
	s_cbranch_scc0 .Lcv_gate_pd1
	s_mul_hi_u32 s0, s47, 0x2e8ba3
	s_mul_i32 s1, s0, 1408
	s_sub_u32 s1, s47, s1
	s_mul_hi_u32 s2, s1, 0x2e8ba2f
	s_mul_i32 s8, s2, 88
	s_sub_u32 s8, s1, s8
	s_mul_i32 s9, s0, 0x2c00000
	s_mul_i32 s28, s2, 0x2c0000
	s_add_u32 s9, s9, s28
	s_lshl_b32 s8, s8, 8
	s_add_u32 s9, s9, s8
	s_add_u32 s42, s70, s9
	s_addc_u32 s43, s71, 0
	s_mov_b32 m0, s48
	s_add_u32 s49, s48, 0x400
	global_load_lds_dwordx4 v0, s[42:43] nt
	s_mov_b32 m0, s49
	s_add_u32 s49, s48, 0x800
	global_load_lds_dwordx4 v1, s[42:43] nt
	s_mov_b32 m0, s49
	s_add_u32 s49, s48, 0xc00
	global_load_lds_dwordx4 v2, s[42:43] nt
	s_mov_b32 m0, s49
	s_nop 0
	global_load_lds_dwordx4 v3, s[42:43] nt
	s_branch .Lcv_gate_pj1

; #define CVT_LOAD(tile_) do { const int k0_ = ((tile_) / ntn) << 7, n0_ = ((tile_) % ntn) << 6; \
;         _Pragma("unroll") for (int pp = 0; pp < 4; ++pp) pv[pp] = *(const float4*)(src + (size_t)(k0_ + lk + 32 * pp) * N + n0_ + ln4); } while (0)
; __device__ __forceinline__ void convT_job(const float* __restrict__ src, bf16_t* __restrict__ dst, int K, int N, int mode, float* t) {
;     ...
;     int tile = blockIdx.x;
;     if (tile < ntiles) CVT_LOAD(tile);
; #pragma unroll 1
;     for (; tile < ntiles; tile += gridDim.x) {
;         const int k0 = (tile / ntn) << 7, n0 = (tile % ntn) << 6;
; #pragma unroll
;         for (int pp = 0; pp < 4; ++pp) { const int k = lk + 32 * pp; t[k * 65 + ln4] = pv[pp].x; t[k * 65 + ln4 + 1] = pv[pp].y; t[k * 65 + ln4 + 2] = pv[pp].z; t[k * 65 + ln4 + 3] = pv[pp].w; }
;         if (tile + (int)gridDim.x < ntiles) CVT_LOAD(tile + (int)gridDim.x);
; __device__ __forceinline__ void phase_convert(const Params& p, unsigned char* smem) {
;     ...
;             convT_job(p.in[3] + wo, gu, 2048, 5632, 1, t);
.Lcv_gate_pj1:
	global_load_dword v24, v173, s[70:71]
	global_load_dword v24, v173, s[70:71]
	s_lshl_b32 s47, s98, 1
	s_add_u32 s47, s47, s40
	s_add_u32 s48, s46, 0x10000
	s_cmp_lt_u32 s47, 1408
	s_cbranch_scc0 .Lcv_gate_pd2
	s_mul_hi_u32 s0, s47, 0x2e8ba3
	s_mul_i32 s1, s0, 1408
	s_sub_u32 s1, s47, s1
	s_mul_hi_u32 s2, s1, 0x2e8ba2f
	s_mul_i32 s8, s2, 88
	s_sub_u32 s8, s1, s8
	s_mul_i32 s9, s0, 0x2c00000
	s_mul_i32 s28, s2, 0x2c0000
	s_add_u32 s9, s9, s28
	s_lshl_b32 s8, s8, 8
	s_add_u32 s9, s9, s8
	s_add_u32 s42, s70, s9
	s_addc_u32 s43, s71, 0
	s_mov_b32 m0, s48
	s_add_u32 s49, s48, 0x400
	global_load_lds_dwordx4 v0, s[42:43] nt
	s_mov_b32 m0, s49
	s_add_u32 s49, s48, 0x800
	global_load_lds_dwordx4 v1, s[42:43] nt
	s_mov_b32 m0, s49
	s_add_u32 s49, s48, 0xc00
	global_load_lds_dwordx4 v2, s[42:43] nt
	s_mov_b32 m0, s49
	s_nop 0
	global_load_lds_dwordx4 v3, s[42:43] nt
	s_branch .Lcv_gate_pj2

; #define CVT_LOAD(tile_) do { const int k0_ = ((tile_) / ntn) << 7, n0_ = ((tile_) % ntn) << 6; \
;         _Pragma("unroll") for (int pp = 0; pp < 4; ++pp) pv[pp] = *(const float4*)(src + (size_t)(k0_ + lk + 32 * pp) * N + n0_ + ln4); } while (0)
; __device__ __forceinline__ void convT_job(const float* __restrict__ src, bf16_t* __restrict__ dst, int K, int N, int mode, float* t) {
;     ...
; #pragma unroll 1
;     for (; tile < ntiles; tile += gridDim.x) {
;         const int k0 = (tile / ntn) << 7, n0 = (tile % ntn) << 6;
; #pragma unroll
;         for (int pp = 0; pp < 4; ++pp) { const int k = lk + 32 * pp; t[k * 65 + ln4] = pv[pp].x; t[k * 65 + ln4 + 1] = pv[pp].y; t[k * 65 + ln4 + 2] = pv[pp].z; t[k * 65 + ln4 + 3] = pv[pp].w; }
;         if (tile + (int)gridDim.x < ntiles) CVT_LOAD(tile + (int)gridDim.x);
; __device__ __forceinline__ void phase_convert(const Params& p, unsigned char* smem) {
;     ...
;             convT_job(p.in[3] + wo, gu, 2048, 5632, 1, t);
.Lcv_gate_loop:
	s_waitcnt vmcnt(14)
	s_barrier
	s_mul_i32 s47, s98, 3
	s_add_u32 s47, s47, s40
	s_add_u32 s48, s41, 0x18000
	s_and_b32 s48, s48, 0x1ffff
	s_add_u32 s48, s48, s46
	s_cmp_lt_u32 s47, 1408
	s_cbranch_scc0 .Lcv_gate_ld
	s_mul_hi_u32 s0, s47, 0x2e8ba3
	s_mul_i32 s1, s0, 1408
	s_sub_u32 s1, s47, s1
	s_mul_hi_u32 s2, s1, 0x2e8ba2f
	s_mul_i32 s8, s2, 88
	s_sub_u32 s8, s1, s8
	s_mul_i32 s9, s0, 0x2c00000
	s_mul_i32 s28, s2, 0x2c0000
	s_add_u32 s9, s9, s28
	s_lshl_b32 s8, s8, 8
	s_add_u32 s9, s9, s8
	s_add_u32 s42, s70, s9
	s_addc_u32 s43, s71, 0
	s_mov_b32 m0, s48
	s_add_u32 s49, s48, 0x400
	global_load_lds_dwordx4 v0, s[42:43] nt
	s_mov_b32 m0, s49
	s_add_u32 s49, s48, 0x800
	global_load_lds_dwordx4 v1, s[42:43] nt
	s_mov_b32 m0, s49
	s_add_u32 s49, s48, 0xc00
	global_load_lds_dwordx4 v2, s[42:43] nt
	s_mov_b32 m0, s49
	s_nop 0
	global_load_lds_dwordx4 v3, s[42:43] nt
	s_branch .Lcv_gate_lj

; __device__ __forceinline__ unsigned cvt_pk_bf16(float lo, float hi) { unsigned r; asm volatile("v_cvt_pk_bf16_f32 %0, %1, %2" : "=v"(r) : "v"(lo), "v"(hi)); return r; }
; __device__ __forceinline__ void lds_barrier() { asm volatile("s_waitcnt lgkmcnt(0)" ::: "memory"); __builtin_amdgcn_s_barrier(); asm volatile("" ::: "memory"); }
; __device__ __forceinline__ void convT_job(const float* __restrict__ src, bf16_t* __restrict__ dst, int K, int N, int mode, float* t) {
;     ...
;         lds_barrier();
;         const int n = tid >> 3, k16 = (tid & 7) * 16;
;         float v[16];
; #pragma unroll
;         for (int j = 0; j < 16; ++j) v[j] = t[(k16 + j) * 65 + n];
;         const int nn = n0 + n;
;         const int row = mode == 0 ? nn : (256 * (nn >> 7) + (nn & 127) + (mode == 2 ? 128 : 0));
;         u32x4 w0, w1; w0.x = cvt_pk_bf16(v[0], v[1]); w0.y = cvt_pk_bf16(v[2], v[3]); w0.z = cvt_pk_bf16(v[4], v[5]); w0.w = cvt_pk_bf16(v[6], v[7]);
;         w1.x = cvt_pk_bf16(v[8], v[9]); w1.y = cvt_pk_bf16(v[10], v[11]); w1.z = cvt_pk_bf16(v[12], v[13]); w1.w = cvt_pk_bf16(v[14], v[15]);
;         bf16_t* d = dst + (size_t)row * K + k0 + k16;
;         *(u32x4*)d = w0; *(u32x4*)(d + 8) = w1;
;         lds_barrier();
; __device__ __forceinline__ void phase_convert(const Params& p, unsigned char* smem) {
;     ...
;             convT_job(p.in[3] + wo, gu, 2048, 5632, 1, t);
;             convT_job(p.in[4] + wo, gu, 2048, 5632, 2, t);
.Lcv_gate_lj:
	v_add_u32_e32 v7, s41, v4
	ds_read2st64_b32 v[8:9], v7 offset0:0 offset1:1
	ds_read2st64_b32 v[10:11], v7 offset0:2 offset1:3
	ds_read2st64_b32 v[12:13], v7 offset0:4 offset1:5
	ds_read2st64_b32 v[14:15], v7 offset0:6 offset1:7
	ds_read2st64_b32 v[16:17], v7 offset0:8 offset1:9
	ds_read2st64_b32 v[18:19], v7 offset0:10 offset1:11
	ds_read2st64_b32 v[20:21], v7 offset0:12 offset1:13
	ds_read2st64_b32 v[22:23], v7 offset0:14 offset1:15
	s_mul_hi_u32 s0, s40, 0x2e8ba3
	s_mul_i32 s1, s0, 1408
	s_sub_u32 s1, s40, s1
	s_mul_hi_u32 s2, s1, 0x2e8ba2f
	s_mul_i32 s8, s2, 88
	s_sub_u32 s8, s1, s8
	s_lshr_b32 s9, s8, 1
	s_lshl_b32 s9, s9, 8
	s_and_b32 s28, s8, 1
	s_lshl_b32 s28, s28, 6
	s_add_u32 s9, s9, s28
	s_mul_i32 s9, s9, 0x1000
	s_mul_i32 s28, s0, 0x2c00000
	s_add_u32 s9, s9, s28
	s_lshl_b32 s2, s2, 8
	s_add_u32 s9, s9, s2
	s_add_u32 s9, s9, 0x8000
	s_add_u32 s44, s54, s9
	s_addc_u32 s45, s55, 0
	s_waitcnt lgkmcnt(6)
	v_cvt_pk_bf16_f32 v8, v8, v9
	v_cvt_pk_bf16_f32 v9, v10, v11
	s_waitcnt lgkmcnt(4)
	v_cvt_pk_bf16_f32 v10, v12, v13
	v_cvt_pk_bf16_f32 v11, v14, v15
	s_waitcnt lgkmcnt(2)
	v_cvt_pk_bf16_f32 v12, v16, v17
	v_cvt_pk_bf16_f32 v13, v18, v19
	s_waitcnt lgkmcnt(0)
	v_cvt_pk_bf16_f32 v14, v20, v21
	v_cvt_pk_bf16_f32 v15, v22, v23
	global_store_dwordx4 v5, v[8:11], s[44:45]
	global_store_dwordx4 v5, v[12:15], s[44:45] offset:16
	s_add_u32 s40, s40, s98
	s_add_u32 s41, s41, 0x8000
	s_and_b32 s41, s41, 0x1ffff
	s_cmp_lt_u32 s40, 1408
	s_cbranch_scc1 .Lcv_gate_loop
.Lcv_gate_skip:
	s_mov_b32 s40, s60
	s_cmp_lt_u32 s40, 1408
	s_cbranch_scc0 .Lcv_up_skip
	v_mov_b32_e32 v29, 0x5800
	v_mov_b32_e32 v28, 0x1000
	v_mad_u32_u24 v0, v30, v29, v31
	v_mad_u32_u24 v5, v26, v28, v27
	v_add_u32_e32 v1, 0x16000, v0
	v_add_u32_e32 v2, 0x2c000, v0
	v_add_u32_e32 v3, 0x42000, v0
	s_barrier
	s_mov_b32 s41, 0
	s_mov_b32 s47, s40
	s_mov_b32 s48, s46
	s_mul_hi_u32 s0, s47, 0x2e8ba3
	s_mul_i32 s1, s0, 1408
	s_sub_u32 s1, s47, s1
	s_mul_hi_u32 s2, s1, 0x2e8ba2f
	s_mul_i32 s8, s2, 88
	s_sub_u32 s8, s1, s8
	s_mul_i32 s9, s0, 0x2c00000
	s_mul_i32 s28, s2, 0x2c0000
	s_add_u32 s9, s9, s28
	s_lshl_b32 s8, s8, 8
	s_add_u32 s9, s9, s8
	s_add_u32 s42, s72, s9
	s_addc_u32 s43, s73, 0
	s_mov_b32 m0, s48
	s_add_u32 s49, s48, 0x400
	global_load_lds_dwordx4 v0, s[42:43] nt
	s_mov_b32 m0, s49
	s_add_u32 s49, s48, 0x800
	global_load_lds_dwordx4 v1, s[42:43] nt
	s_mov_b32 m0, s49
	s_add_u32 s49, s48, 0xc00
	global_load_lds_dwordx4 v2, s[42:43] nt
	s_mov_b32 m0, s49
	s_nop 0
	global_load_lds_dwordx4 v3, s[42:43] nt
	global_load_dword v24, v173, s[72:73]
	global_load_dword v24, v173, s[72:73]
	s_add_u32 s47, s40, s98
	s_add_u32 s48, s46, 0x8000
	s_cmp_lt_u32 s47, 1408
	s_cbranch_scc0 .Lcv_up_pd1
	s_mul_hi_u32 s0, s47, 0x2e8ba3
	s_mul_i32 s1, s0, 1408
	s_sub_u32 s1, s47, s1
	s_mul_hi_u32 s2, s1, 0x2e8ba2f
	s_mul_i32 s8, s2, 88
	s_sub_u32 s8, s1, s8
	s_mul_i32 s9, s0, 0x2c00000
	s_mul_i32 s28, s2, 0x2c0000
	s_add_u32 s9, s9, s28
	s_lshl_b32 s8, s8, 8
	s_add_u32 s9, s9, s8
	s_add_u32 s42, s72, s9
	s_addc_u32 s43, s73, 0
	s_mov_b32 m0, s48
	s_add_u32 s49, s48, 0x400
	global_load_lds_dwordx4 v0, s[42:43] nt
	s_mov_b32 m0, s49
	s_add_u32 s49, s48, 0x800
	global_load_lds_dwordx4 v1, s[42:43] nt
	s_mov_b32 m0, s49
	s_add_u32 s49, s48, 0xc00
	global_load_lds_dwordx4 v2, s[42:43] nt
	s_mov_b32 m0, s49
	s_nop 0
	global_load_lds_dwordx4 v3, s[42:43] nt
	s_branch .Lcv_up_pj1

; #define CVT_LOAD(tile_) do { const int k0_ = ((tile_) / ntn) << 7, n0_ = ((tile_) % ntn) << 6; \
;         _Pragma("unroll") for (int pp = 0; pp < 4; ++pp) pv[pp] = *(const float4*)(src + (size_t)(k0_ + lk + 32 * pp) * N + n0_ + ln4); } while (0)
; __device__ __forceinline__ void convT_job(const float* __restrict__ src, bf16_t* __restrict__ dst, int K, int N, int mode, float* t) {
;     ...
;     int tile = blockIdx.x;
;     if (tile < ntiles) CVT_LOAD(tile);
; #pragma unroll 1
;     for (; tile < ntiles; tile += gridDim.x) {
;         const int k0 = (tile / ntn) << 7, n0 = (tile % ntn) << 6;
; #pragma unroll
;         for (int pp = 0; pp < 4; ++pp) { const int k = lk + 32 * pp; t[k * 65 + ln4] = pv[pp].x; t[k * 65 + ln4 + 1] = pv[pp].y; t[k * 65 + ln4 + 2] = pv[pp].z; t[k * 65 + ln4 + 3] = pv[pp].w; }
;         if (tile + (int)gridDim.x < ntiles) CVT_LOAD(tile + (int)gridDim.x);
; __device__ __forceinline__ void phase_convert(const Params& p, unsigned char* smem) {
;     ...
;             convT_job(p.in[4] + wo, gu, 2048, 5632, 2, t);
.Lcv_up_pj1:
	global_load_dword v24, v173, s[72:73]
	global_load_dword v24, v173, s[72:73]
	s_lshl_b32 s47, s98, 1
	s_add_u32 s47, s47, s40
	s_add_u32 s48, s46, 0x10000
	s_cmp_lt_u32 s47, 1408
	s_cbranch_scc0 .Lcv_up_pd2
	s_mul_hi_u32 s0, s47, 0x2e8ba3
	s_mul_i32 s1, s0, 1408
	s_sub_u32 s1, s47, s1
	s_mul_hi_u32 s2, s1, 0x2e8ba2f
	s_mul_i32 s8, s2, 88
	s_sub_u32 s8, s1, s8
	s_mul_i32 s9, s0, 0x2c00000
	s_mul_i32 s28, s2, 0x2c0000
	s_add_u32 s9, s9, s28
	s_lshl_b32 s8, s8, 8
	s_add_u32 s9, s9, s8
	s_add_u32 s42, s72, s9
	s_addc_u32 s43, s73, 0
	s_mov_b32 m0, s48
	s_add_u32 s49, s48, 0x400
	global_load_lds_dwordx4 v0, s[42:43] nt
	s_mov_b32 m0, s49
	s_add_u32 s49, s48, 0x800
	global_load_lds_dwordx4 v1, s[42:43] nt
	s_mov_b32 m0, s49
	s_add_u32 s49, s48, 0xc00
	global_load_lds_dwordx4 v2, s[42:43] nt
	s_mov_b32 m0, s49
	s_nop 0
	global_load_lds_dwordx4 v3, s[42:43] nt
	s_branch .Lcv_up_pj2

; #define CVT_LOAD(tile_) do { const int k0_ = ((tile_) / ntn) << 7, n0_ = ((tile_) % ntn) << 6; \
;         _Pragma("unroll") for (int pp = 0; pp < 4; ++pp) pv[pp] = *(const float4*)(src + (size_t)(k0_ + lk + 32 * pp) * N + n0_ + ln4); } while (0)
; __device__ __forceinline__ void convT_job(const float* __restrict__ src, bf16_t* __restrict__ dst, int K, int N, int mode, float* t) {
;     ...
; #pragma unroll 1
;     for (; tile < ntiles; tile += gridDim.x) {
;         const int k0 = (tile / ntn) << 7, n0 = (tile % ntn) << 6;
; #pragma unroll
;         for (int pp = 0; pp < 4; ++pp) { const int k = lk + 32 * pp; t[k * 65 + ln4] = pv[pp].x; t[k * 65 + ln4 + 1] = pv[pp].y; t[k * 65 + ln4 + 2] = pv[pp].z; t[k * 65 + ln4 + 3] = pv[pp].w; }
;         if (tile + (int)gridDim.x < ntiles) CVT_LOAD(tile + (int)gridDim.x);
; __device__ __forceinline__ void phase_convert(const Params& p, unsigned char* smem) {
;     ...
;             convT_job(p.in[4] + wo, gu, 2048, 5632, 2, t);
.Lcv_up_loop:
	s_waitcnt vmcnt(14)
	s_barrier
	s_mul_i32 s47, s98, 3
	s_add_u32 s47, s47, s40
	s_add_u32 s48, s41, 0x18000
	s_and_b32 s48, s48, 0x1ffff
	s_add_u32 s48, s48, s46
	s_cmp_lt_u32 s47, 1408
	s_cbranch_scc0 .Lcv_up_ld
	s_mul_hi_u32 s0, s47, 0x2e8ba3
	s_mul_i32 s1, s0, 1408
	s_sub_u32 s1, s47, s1
	s_mul_hi_u32 s2, s1, 0x2e8ba2f
	s_mul_i32 s8, s2, 88
	s_sub_u32 s8, s1, s8
	s_mul_i32 s9, s0, 0x2c00000
	s_mul_i32 s28, s2, 0x2c0000
	s_add_u32 s9, s9, s28
	s_lshl_b32 s8, s8, 8
	s_add_u32 s9, s9, s8
	s_add_u32 s42, s72, s9
	s_addc_u32 s43, s73, 0
	s_mov_b32 m0, s48
	s_add_u32 s49, s48, 0x400
	global_load_lds_dwordx4 v0, s[42:43] nt
	s_mov_b32 m0, s49
	s_add_u32 s49, s48, 0x800
	global_load_lds_dwordx4 v1, s[42:43] nt
	s_mov_b32 m0, s49
	s_add_u32 s49, s48, 0xc00
	global_load_lds_dwordx4 v2, s[42:43] nt
	s_mov_b32 m0, s49
	s_nop 0
	global_load_lds_dwordx4 v3, s[42:43] nt
	s_branch .Lcv_up_lj

; __device__ __forceinline__ unsigned cvt_pk_bf16(float lo, float hi) { unsigned r; asm volatile("v_cvt_pk_bf16_f32 %0, %1, %2" : "=v"(r) : "v"(lo), "v"(hi)); return r; }
; __device__ __forceinline__ void lds_barrier() { asm volatile("s_waitcnt lgkmcnt(0)" ::: "memory"); __builtin_amdgcn_s_barrier(); asm volatile("" ::: "memory"); }
; __device__ __forceinline__ void convT_job(const float* __restrict__ src, bf16_t* __restrict__ dst, int K, int N, int mode, float* t) {
;     ...
;         lds_barrier();
;         const int n = tid >> 3, k16 = (tid & 7) * 16;
;         float v[16];
; #pragma unroll
;         for (int j = 0; j < 16; ++j) v[j] = t[(k16 + j) * 65 + n];
;         const int nn = n0 + n;
;         const int row = mode == 0 ? nn : (256 * (nn >> 7) + (nn & 127) + (mode == 2 ? 128 : 0));
;         u32x4 w0, w1; w0.x = cvt_pk_bf16(v[0], v[1]); w0.y = cvt_pk_bf16(v[2], v[3]); w0.z = cvt_pk_bf16(v[4], v[5]); w0.w = cvt_pk_bf16(v[6], v[7]);
;         w1.x = cvt_pk_bf16(v[8], v[9]); w1.y = cvt_pk_bf16(v[10], v[11]); w1.z = cvt_pk_bf16(v[12], v[13]); w1.w = cvt_pk_bf16(v[14], v[15]);
;         bf16_t* d = dst + (size_t)row * K + k0 + k16;
;         *(u32x4*)d = w0; *(u32x4*)(d + 8) = w1;
;         lds_barrier();
; __device__ __forceinline__ void phase_convert(const Params& p, unsigned char* smem) {
;     ...
;             convT_job(p.in[4] + wo, gu, 2048, 5632, 2, t);
;             convT_job(p.in[5] + wo, (bf16_t*)(p.ws + OFF_DN + (size_t)(l * 2 + f) * SZ_DN), 5632, 2048, 0, t);
.Lcv_up_lj:
	v_add_u32_e32 v7, s41, v4
	ds_read2st64_b32 v[8:9], v7 offset0:0 offset1:1
	ds_read2st64_b32 v[10:11], v7 offset0:2 offset1:3
	ds_read2st64_b32 v[12:13], v7 offset0:4 offset1:5
	ds_read2st64_b32 v[14:15], v7 offset0:6 offset1:7
	ds_read2st64_b32 v[16:17], v7 offset0:8 offset1:9
	ds_read2st64_b32 v[18:19], v7 offset0:10 offset1:11
	ds_read2st64_b32 v[20:21], v7 offset0:12 offset1:13
	ds_read2st64_b32 v[22:23], v7 offset0:14 offset1:15
	s_mul_hi_u32 s0, s40, 0x2e8ba3
	s_mul_i32 s1, s0, 1408
	s_sub_u32 s1, s40, s1
	s_mul_hi_u32 s2, s1, 0x2e8ba2f
	s_mul_i32 s8, s2, 88
	s_sub_u32 s8, s1, s8
	s_lshr_b32 s9, s8, 1
	s_lshl_b32 s9, s9, 8
	s_and_b32 s28, s8, 1
	s_lshl_b32 s28, s28, 6
	s_add_u32 s9, s9, s28
	s_add_u32 s9, s9, 128
	s_mul_i32 s9, s9, 0x1000
	s_mul_i32 s28, s0, 0x2c00000
	s_add_u32 s9, s9, s28
	s_lshl_b32 s2, s2, 8
	s_add_u32 s9, s9, s2
	s_add_u32 s9, s9, 0x8000
	s_add_u32 s44, s54, s9
	s_addc_u32 s45, s55, 0
	s_waitcnt lgkmcnt(6)
	v_cvt_pk_bf16_f32 v8, v8, v9
	v_cvt_pk_bf16_f32 v9, v10, v11
	s_waitcnt lgkmcnt(4)
	v_cvt_pk_bf16_f32 v10, v12, v13
	v_cvt_pk_bf16_f32 v11, v14, v15
	s_waitcnt lgkmcnt(2)
	v_cvt_pk_bf16_f32 v12, v16, v17
	v_cvt_pk_bf16_f32 v13, v18, v19
	s_waitcnt lgkmcnt(0)
	v_cvt_pk_bf16_f32 v14, v20, v21
	v_cvt_pk_bf16_f32 v15, v22, v23
	global_store_dwordx4 v5, v[8:11], s[44:45]
	global_store_dwordx4 v5, v[12:15], s[44:45] offset:16
	s_add_u32 s40, s40, s98
	s_add_u32 s41, s41, 0x8000
	s_and_b32 s41, s41, 0x1ffff
	s_cmp_lt_u32 s40, 1408
	s_cbranch_scc1 .Lcv_up_loop
.Lcv_up_skip:
	s_mov_b32 s40, s60
	s_cmp_lt_u32 s40, 1408
	s_cbranch_scc0 .Lcv_down_skip
	v_mov_b32_e32 v29, 0x2000
	v_mov_b32_e32 v28, 0x2c00
	v_mad_u32_u24 v0, v30, v29, v31
	v_mad_u32_u24 v5, v26, v28, v27
	v_add_u32_e32 v1, 0x8000, v0
	v_add_u32_e32 v2, 0x10000, v0
	v_add_u32_e32 v3, 0x18000, v0
	s_barrier
	s_mov_b32 s41, 0
	s_mov_b32 s47, s40
	s_mov_b32 s48, s46
	s_mul_hi_u32 s0, s47, 0x2e8ba3
	s_mul_i32 s1, s0, 1408
	s_sub_u32 s1, s47, s1
	s_mul_hi_u32 s2, s1, 0x8000001
	s_mul_i32 s8, s2, 32
	s_sub_u32 s8, s1, s8
	s_mul_i32 s9, s0, 0x2c00000
	s_mul_i32 s28, s2, 0x100000
	s_add_u32 s9, s9, s28
	s_lshl_b32 s8, s8, 8
	s_add_u32 s9, s9, s8
	s_add_u32 s42, s74, s9
	s_addc_u32 s43, s75, 0
	s_mov_b32 m0, s48
	s_add_u32 s49, s48, 0x400
	global_load_lds_dwordx4 v0, s[42:43] nt
	s_mov_b32 m0, s49
	s_add_u32 s49, s48, 0x800
	global_load_lds_dwordx4 v1, s[42:43] nt
	s_mov_b32 m0, s49
	s_add_u32 s49, s48, 0xc00
	global_load_lds_dwordx4 v2, s[42:43] nt
	s_mov_b32 m0, s49
	s_nop 0
	global_load_lds_dwordx4 v3, s[42:43] nt
	global_load_dword v24, v173, s[74:75]
	global_load_dword v24, v173, s[74:75]
	s_add_u32 s47, s40, s98
	s_add_u32 s48, s46, 0x8000
	s_cmp_lt_u32 s47, 1408
	s_cbranch_scc0 .Lcv_down_pd1
	s_mul_hi_u32 s0, s47, 0x2e8ba3
	s_mul_i32 s1, s0, 1408
	s_sub_u32 s1, s47, s1
	s_mul_hi_u32 s2, s1, 0x8000001
	s_mul_i32 s8, s2, 32
	s_sub_u32 s8, s1, s8
	s_mul_i32 s9, s0, 0x2c00000
	s_mul_i32 s28, s2, 0x100000
	s_add_u32 s9, s9, s28
	s_lshl_b32 s8, s8, 8
	s_add_u32 s9, s9, s8
	s_add_u32 s42, s74, s9
	s_addc_u32 s43, s75, 0
	s_mov_b32 m0, s48
	s_add_u32 s49, s48, 0x400
	global_load_lds_dwordx4 v0, s[42:43] nt
	s_mov_b32 m0, s49
	s_add_u32 s49, s48, 0x800
	global_load_lds_dwordx4 v1, s[42:43] nt
	s_mov_b32 m0, s49
	s_add_u32 s49, s48, 0xc00
	global_load_lds_dwordx4 v2, s[42:43] nt
	s_mov_b32 m0, s49
	s_nop 0
	global_load_lds_dwordx4 v3, s[42:43] nt
	s_branch .Lcv_down_pj1

; #define CVT_LOAD(tile_) do { const int k0_ = ((tile_) / ntn) << 7, n0_ = ((tile_) % ntn) << 6; \
;         _Pragma("unroll") for (int pp = 0; pp < 4; ++pp) pv[pp] = *(const float4*)(src + (size_t)(k0_ + lk + 32 * pp) * N + n0_ + ln4); } while (0)
; __device__ __forceinline__ void convT_job(const float* __restrict__ src, bf16_t* __restrict__ dst, int K, int N, int mode, float* t) {
;     ...
;     int tile = blockIdx.x;
;     if (tile < ntiles) CVT_LOAD(tile);
; #pragma unroll 1
;     for (; tile < ntiles; tile += gridDim.x) {
;         const int k0 = (tile / ntn) << 7, n0 = (tile % ntn) << 6;
; #pragma unroll
;         for (int pp = 0; pp < 4; ++pp) { const int k = lk + 32 * pp; t[k * 65 + ln4] = pv[pp].x; t[k * 65 + ln4 + 1] = pv[pp].y; t[k * 65 + ln4 + 2] = pv[pp].z; t[k * 65 + ln4 + 3] = pv[pp].w; }
;         if (tile + (int)gridDim.x < ntiles) CVT_LOAD(tile + (int)gridDim.x);
; __device__ __forceinline__ void phase_convert(const Params& p, unsigned char* smem) {
;     ...
;             convT_job(p.in[5] + wo, (bf16_t*)(p.ws + OFF_DN + (size_t)(l * 2 + f) * SZ_DN), 5632, 2048, 0, t);
.Lcv_down_pj1:
	global_load_dword v24, v173, s[74:75]
	global_load_dword v24, v173, s[74:75]
	s_lshl_b32 s47, s98, 1
	s_add_u32 s47, s47, s40
	s_add_u32 s48, s46, 0x10000
	s_cmp_lt_u32 s47, 1408
	s_cbranch_scc0 .Lcv_down_pd2
	s_mul_hi_u32 s0, s47, 0x2e8ba3
	s_mul_i32 s1, s0, 1408
	s_sub_u32 s1, s47, s1
	s_mul_hi_u32 s2, s1, 0x8000001
	s_mul_i32 s8, s2, 32
	s_sub_u32 s8, s1, s8
	s_mul_i32 s9, s0, 0x2c00000
	s_mul_i32 s28, s2, 0x100000
	s_add_u32 s9, s9, s28
	s_lshl_b32 s8, s8, 8
	s_add_u32 s9, s9, s8
	s_add_u32 s42, s74, s9
	s_addc_u32 s43, s75, 0
	s_mov_b32 m0, s48
	s_add_u32 s49, s48, 0x400
	global_load_lds_dwordx4 v0, s[42:43] nt
	s_mov_b32 m0, s49
	s_add_u32 s49, s48, 0x800
	global_load_lds_dwordx4 v1, s[42:43] nt
	s_mov_b32 m0, s49
	s_add_u32 s49, s48, 0xc00
	global_load_lds_dwordx4 v2, s[42:43] nt
	s_mov_b32 m0, s49
	s_nop 0
	global_load_lds_dwordx4 v3, s[42:43] nt
	s_branch .Lcv_down_pj2

; #define CVT_LOAD(tile_) do { const int k0_ = ((tile_) / ntn) << 7, n0_ = ((tile_) % ntn) << 6; \
;         _Pragma("unroll") for (int pp = 0; pp < 4; ++pp) pv[pp] = *(const float4*)(src + (size_t)(k0_ + lk + 32 * pp) * N + n0_ + ln4); } while (0)
; __device__ __forceinline__ void convT_job(const float* __restrict__ src, bf16_t* __restrict__ dst, int K, int N, int mode, float* t) {
;     ...
; #pragma unroll 1
;     for (; tile < ntiles; tile += gridDim.x) {
;         const int k0 = (tile / ntn) << 7, n0 = (tile % ntn) << 6;
; #pragma unroll
;         for (int pp = 0; pp < 4; ++pp) { const int k = lk + 32 * pp; t[k * 65 + ln4] = pv[pp].x; t[k * 65 + ln4 + 1] = pv[pp].y; t[k * 65 + ln4 + 2] = pv[pp].z; t[k * 65 + ln4 + 3] = pv[pp].w; }
;         if (tile + (int)gridDim.x < ntiles) CVT_LOAD(tile + (int)gridDim.x);
; __device__ __forceinline__ void phase_convert(const Params& p, unsigned char* smem) {
;     ...
;             convT_job(p.in[5] + wo, (bf16_t*)(p.ws + OFF_DN + (size_t)(l * 2 + f) * SZ_DN), 5632, 2048, 0, t);
.Lcv_down_loop:
	s_waitcnt vmcnt(14)
	s_barrier
	s_mul_i32 s47, s98, 3
	s_add_u32 s47, s47, s40
	s_add_u32 s48, s41, 0x18000
	s_and_b32 s48, s48, 0x1ffff
	s_add_u32 s48, s48, s46
	s_cmp_lt_u32 s47, 1408
	s_cbranch_scc0 .Lcv_down_ld
	s_mul_hi_u32 s0, s47, 0x2e8ba3
	s_mul_i32 s1, s0, 1408
	s_sub_u32 s1, s47, s1
	s_mul_hi_u32 s2, s1, 0x8000001
	s_mul_i32 s8, s2, 32
	s_sub_u32 s8, s1, s8
	s_mul_i32 s9, s0, 0x2c00000
	s_mul_i32 s28, s2, 0x100000
	s_add_u32 s9, s9, s28
	s_lshl_b32 s8, s8, 8
	s_add_u32 s9, s9, s8
	s_add_u32 s42, s74, s9
	s_addc_u32 s43, s75, 0
	s_mov_b32 m0, s48
	s_add_u32 s49, s48, 0x400
	global_load_lds_dwordx4 v0, s[42:43] nt
	s_mov_b32 m0, s49
	s_add_u32 s49, s48, 0x800
	global_load_lds_dwordx4 v1, s[42:43] nt
	s_mov_b32 m0, s49
	s_add_u32 s49, s48, 0xc00
	global_load_lds_dwordx4 v2, s[42:43] nt
	s_mov_b32 m0, s49
	s_nop 0
	global_load_lds_dwordx4 v3, s[42:43] nt
	s_branch .Lcv_down_lj

; __device__ __forceinline__ unsigned cvt_pk_bf16(float lo, float hi) { unsigned r; asm volatile("v_cvt_pk_bf16_f32 %0, %1, %2" : "=v"(r) : "v"(lo), "v"(hi)); return r; }
; __device__ __forceinline__ void lds_barrier() { asm volatile("s_waitcnt lgkmcnt(0)" ::: "memory"); __builtin_amdgcn_s_barrier(); asm volatile("" ::: "memory"); }
; __device__ __forceinline__ void convT_job(const float* __restrict__ src, bf16_t* __restrict__ dst, int K, int N, int mode, float* t) {
;     ...
;         lds_barrier();
;         const int n = tid >> 3, k16 = (tid & 7) * 16;
;         float v[16];
; #pragma unroll
;         for (int j = 0; j < 16; ++j) v[j] = t[(k16 + j) * 65 + n];
;         const int nn = n0 + n;
;         const int row = mode == 0 ? nn : (256 * (nn >> 7) + (nn & 127) + (mode == 2 ? 128 : 0));
;         u32x4 w0, w1; w0.x = cvt_pk_bf16(v[0], v[1]); w0.y = cvt_pk_bf16(v[2], v[3]); w0.z = cvt_pk_bf16(v[4], v[5]); w0.w = cvt_pk_bf16(v[6], v[7]);
;         w1.x = cvt_pk_bf16(v[8], v[9]); w1.y = cvt_pk_bf16(v[10], v[11]); w1.z = cvt_pk_bf16(v[12], v[13]); w1.w = cvt_pk_bf16(v[14], v[15]);
;         bf16_t* d = dst + (size_t)row * K + k0 + k16;
;         *(u32x4*)d = w0; *(u32x4*)(d + 8) = w1;
;         lds_barrier();
; __device__ __forceinline__ void phase_convert(const Params& p, unsigned char* smem) {
;     ...
;             convT_job(p.in[5] + wo, (bf16_t*)(p.ws + OFF_DN + (size_t)(l * 2 + f) * SZ_DN), 5632, 2048, 0, t);
;         }
;         convT_job(p.in[6] + (size_t)l * 2048 * 5632, (bf16_t*)(p.ws + OFF_IN + (size_t)l * SZ_IN), 2048, 5632, 0, t);
.Lcv_down_lj:
	v_add_u32_e32 v7, s41, v4
	ds_read2st64_b32 v[8:9], v7 offset0:0 offset1:1
	ds_read2st64_b32 v[10:11], v7 offset0:2 offset1:3
	ds_read2st64_b32 v[12:13], v7 offset0:4 offset1:5
	ds_read2st64_b32 v[14:15], v7 offset0:6 offset1:7
	ds_read2st64_b32 v[16:17], v7 offset0:8 offset1:9
	ds_read2st64_b32 v[18:19], v7 offset0:10 offset1:11
	ds_read2st64_b32 v[20:21], v7 offset0:12 offset1:13
	ds_read2st64_b32 v[22:23], v7 offset0:14 offset1:15
	s_mul_hi_u32 s0, s40, 0x2e8ba3
	s_mul_i32 s1, s0, 1408
	s_sub_u32 s1, s40, s1
	s_mul_hi_u32 s2, s1, 0x8000001
	s_mul_i32 s8, s2, 32
	s_sub_u32 s8, s1, s8
	s_lshl_b32 s9, s8, 6
	s_mul_i32 s9, s9, 0x2c00
	s_mul_i32 s28, s0, 0x1600000
	s_add_u32 s9, s9, s28
	s_lshl_b32 s2, s2, 8
	s_add_u32 s9, s9, s2
	s_add_u32 s9, s9, 0xb008000
	s_add_u32 s44, s54, s9
	s_addc_u32 s45, s55, 0
	s_waitcnt lgkmcnt(6)
	v_cvt_pk_bf16_f32 v8, v8, v9
	v_cvt_pk_bf16_f32 v9, v10, v11
	s_waitcnt lgkmcnt(4)
	v_cvt_pk_bf16_f32 v10, v12, v13
	v_cvt_pk_bf16_f32 v11, v14, v15
	s_waitcnt lgkmcnt(2)
	v_cvt_pk_bf16_f32 v12, v16, v17
	v_cvt_pk_bf16_f32 v13, v18, v19
	s_waitcnt lgkmcnt(0)
	v_cvt_pk_bf16_f32 v14, v20, v21
	v_cvt_pk_bf16_f32 v15, v22, v23
	global_store_dwordx4 v5, v[8:11], s[44:45]
	global_store_dwordx4 v5, v[12:15], s[44:45] offset:16
	s_add_u32 s40, s40, s98
	s_add_u32 s41, s41, 0x8000
	s_and_b32 s41, s41, 0x1ffff
	s_cmp_lt_u32 s40, 1408
	s_cbranch_scc1 .Lcv_down_loop
.Lcv_down_skip:
	s_mov_b32 s40, s60
	s_cmp_lt_u32 s40, 1408
	s_cbranch_scc0 .Lcv_win_skip
	v_mov_b32_e32 v29, 0x5800
	v_mov_b32_e32 v28, 0x1000
	v_mad_u32_u24 v0, v30, v29, v31
	v_mad_u32_u24 v5, v26, v28, v27
	v_add_u32_e32 v1, 0x16000, v0
	v_add_u32_e32 v2, 0x2c000, v0
	v_add_u32_e32 v3, 0x42000, v0
	s_barrier
	s_mov_b32 s41, 0
	s_mov_b32 s47, s40
	s_mov_b32 s48, s46
	s_mul_hi_u32 s0, s47, 0x2e8ba3
	s_mul_i32 s1, s0, 1408
	s_sub_u32 s1, s47, s1
	s_mul_hi_u32 s2, s1, 0x2e8ba2f
	s_mul_i32 s8, s2, 88
	s_sub_u32 s8, s1, s8
	s_mul_i32 s9, s0, 0x2c00000
	s_mul_i32 s28, s2, 0x2c0000
	s_add_u32 s9, s9, s28
	s_lshl_b32 s8, s8, 8
	s_add_u32 s9, s9, s8
	s_add_u32 s42, s76, s9
	s_addc_u32 s43, s77, 0
	s_mov_b32 m0, s48
	s_add_u32 s49, s48, 0x400
	global_load_lds_dwordx4 v0, s[42:43] nt
	s_mov_b32 m0, s49
	s_add_u32 s49, s48, 0x800
	global_load_lds_dwordx4 v1, s[42:43] nt
	s_mov_b32 m0, s49
	s_add_u32 s49, s48, 0xc00
	global_load_lds_dwordx4 v2, s[42:43] nt
	s_mov_b32 m0, s49
	s_nop 0
	global_load_lds_dwordx4 v3, s[42:43] nt
	global_load_dword v24, v173, s[76:77]
	global_load_dword v24, v173, s[76:77]
	s_add_u32 s47, s40, s98
	s_add_u32 s48, s46, 0x8000
	s_cmp_lt_u32 s47, 1408
	s_cbranch_scc0 .Lcv_win_pd1
	s_mul_hi_u32 s0, s47, 0x2e8ba3
	s_mul_i32 s1, s0, 1408
	s_sub_u32 s1, s47, s1
	s_mul_hi_u32 s2, s1, 0x2e8ba2f
	s_mul_i32 s8, s2, 88
	s_sub_u32 s8, s1, s8
	s_mul_i32 s9, s0, 0x2c00000
	s_mul_i32 s28, s2, 0x2c0000
	s_add_u32 s9, s9, s28
	s_lshl_b32 s8, s8, 8
	s_add_u32 s9, s9, s8
	s_add_u32 s42, s76, s9
	s_addc_u32 s43, s77, 0
	s_mov_b32 m0, s48
	s_add_u32 s49, s48, 0x400
	global_load_lds_dwordx4 v0, s[42:43] nt
	s_mov_b32 m0, s49
	s_add_u32 s49, s48, 0x800
	global_load_lds_dwordx4 v1, s[42:43] nt
	s_mov_b32 m0, s49
	s_add_u32 s49, s48, 0xc00
	global_load_lds_dwordx4 v2, s[42:43] nt
	s_mov_b32 m0, s49
	s_nop 0
	global_load_lds_dwordx4 v3, s[42:43] nt
	s_branch .Lcv_win_pj1

; #define CVT_LOAD(tile_) do { const int k0_ = ((tile_) / ntn) << 7, n0_ = ((tile_) % ntn) << 6; \
;         _Pragma("unroll") for (int pp = 0; pp < 4; ++pp) pv[pp] = *(const float4*)(src + (size_t)(k0_ + lk + 32 * pp) * N + n0_ + ln4); } while (0)
; __device__ __forceinline__ void convT_job(const float* __restrict__ src, bf16_t* __restrict__ dst, int K, int N, int mode, float* t) {
;     ...
;     int tile = blockIdx.x;
;     if (tile < ntiles) CVT_LOAD(tile);
; #pragma unroll 1
;     for (; tile < ntiles; tile += gridDim.x) {
;         const int k0 = (tile / ntn) << 7, n0 = (tile % ntn) << 6;
; #pragma unroll
;         for (int pp = 0; pp < 4; ++pp) { const int k = lk + 32 * pp; t[k * 65 + ln4] = pv[pp].x; t[k * 65 + ln4 + 1] = pv[pp].y; t[k * 65 + ln4 + 2] = pv[pp].z; t[k * 65 + ln4 + 3] = pv[pp].w; }
;         if (tile + (int)gridDim.x < ntiles) CVT_LOAD(tile + (int)gridDim.x);
; __device__ __forceinline__ void phase_convert(const Params& p, unsigned char* smem) {
;     ...
;         convT_job(p.in[6] + (size_t)l * 2048 * 5632, (bf16_t*)(p.ws + OFF_IN + (size_t)l * SZ_IN), 2048, 5632, 0, t);
.Lcv_win_pj1:
	global_load_dword v24, v173, s[76:77]
	global_load_dword v24, v173, s[76:77]
	s_lshl_b32 s47, s98, 1
	s_add_u32 s47, s47, s40
	s_add_u32 s48, s46, 0x10000
	s_cmp_lt_u32 s47, 1408
	s_cbranch_scc0 .Lcv_win_pd2
	s_mul_hi_u32 s0, s47, 0x2e8ba3
	s_mul_i32 s1, s0, 1408
	s_sub_u32 s1, s47, s1
	s_mul_hi_u32 s2, s1, 0x2e8ba2f
	s_mul_i32 s8, s2, 88
	s_sub_u32 s8, s1, s8
	s_mul_i32 s9, s0, 0x2c00000
	s_mul_i32 s28, s2, 0x2c0000
	s_add_u32 s9, s9, s28
	s_lshl_b32 s8, s8, 8
	s_add_u32 s9, s9, s8
	s_add_u32 s42, s76, s9
	s_addc_u32 s43, s77, 0
	s_mov_b32 m0, s48
	s_add_u32 s49, s48, 0x400
	global_load_lds_dwordx4 v0, s[42:43] nt
	s_mov_b32 m0, s49
	s_add_u32 s49, s48, 0x800
	global_load_lds_dwordx4 v1, s[42:43] nt
	s_mov_b32 m0, s49
	s_add_u32 s49, s48, 0xc00
	global_load_lds_dwordx4 v2, s[42:43] nt
	s_mov_b32 m0, s49
	s_nop 0
	global_load_lds_dwordx4 v3, s[42:43] nt
	s_branch .Lcv_win_pj2

; #define CVT_LOAD(tile_) do { const int k0_ = ((tile_) / ntn) << 7, n0_ = ((tile_) % ntn) << 6; \
;         _Pragma("unroll") for (int pp = 0; pp < 4; ++pp) pv[pp] = *(const float4*)(src + (size_t)(k0_ + lk + 32 * pp) * N + n0_ + ln4); } while (0)
; __device__ __forceinline__ void convT_job(const float* __restrict__ src, bf16_t* __restrict__ dst, int K, int N, int mode, float* t) {
;     ...
; #pragma unroll 1
;     for (; tile < ntiles; tile += gridDim.x) {
;         const int k0 = (tile / ntn) << 7, n0 = (tile % ntn) << 6;
; #pragma unroll
;         for (int pp = 0; pp < 4; ++pp) { const int k = lk + 32 * pp; t[k * 65 + ln4] = pv[pp].x; t[k * 65 + ln4 + 1] = pv[pp].y; t[k * 65 + ln4 + 2] = pv[pp].z; t[k * 65 + ln4 + 3] = pv[pp].w; }
;         if (tile + (int)gridDim.x < ntiles) CVT_LOAD(tile + (int)gridDim.x);
; __device__ __forceinline__ void phase_convert(const Params& p, unsigned char* smem) {
;     ...
;         convT_job(p.in[6] + (size_t)l * 2048 * 5632, (bf16_t*)(p.ws + OFF_IN + (size_t)l * SZ_IN), 2048, 5632, 0, t);
.Lcv_win_loop:
	s_waitcnt vmcnt(14)
	s_barrier
	s_mul_i32 s47, s98, 3
	s_add_u32 s47, s47, s40
	s_add_u32 s48, s41, 0x18000
	s_and_b32 s48, s48, 0x1ffff
	s_add_u32 s48, s48, s46
	s_cmp_lt_u32 s47, 1408
	s_cbranch_scc0 .Lcv_win_ld
	s_mul_hi_u32 s0, s47, 0x2e8ba3
	s_mul_i32 s1, s0, 1408
	s_sub_u32 s1, s47, s1
	s_mul_hi_u32 s2, s1, 0x2e8ba2f
	s_mul_i32 s8, s2, 88
	s_sub_u32 s8, s1, s8
	s_mul_i32 s9, s0, 0x2c00000
	s_mul_i32 s28, s2, 0x2c0000
	s_add_u32 s9, s9, s28
	s_lshl_b32 s8, s8, 8
	s_add_u32 s9, s9, s8
	s_add_u32 s42, s76, s9
	s_addc_u32 s43, s77, 0
	s_mov_b32 m0, s48
	s_add_u32 s49, s48, 0x400
	global_load_lds_dwordx4 v0, s[42:43] nt
	s_mov_b32 m0, s49
	s_add_u32 s49, s48, 0x800
	global_load_lds_dwordx4 v1, s[42:43] nt
	s_mov_b32 m0, s49
	s_add_u32 s49, s48, 0xc00
	global_load_lds_dwordx4 v2, s[42:43] nt
	s_mov_b32 m0, s49
	s_nop 0
	global_load_lds_dwordx4 v3, s[42:43] nt
	s_branch .Lcv_win_lj

; __device__ __forceinline__ unsigned cvt_pk_bf16(float lo, float hi) { unsigned r; asm volatile("v_cvt_pk_bf16_f32 %0, %1, %2" : "=v"(r) : "v"(lo), "v"(hi)); return r; }
; __device__ __forceinline__ void lds_barrier() { asm volatile("s_waitcnt lgkmcnt(0)" ::: "memory"); __builtin_amdgcn_s_barrier(); asm volatile("" ::: "memory"); }
; __device__ __forceinline__ void convT_job(const float* __restrict__ src, bf16_t* __restrict__ dst, int K, int N, int mode, float* t) {
;     ...
;         lds_barrier();
;         const int n = tid >> 3, k16 = (tid & 7) * 16;
;         float v[16];
; #pragma unroll
;         for (int j = 0; j < 16; ++j) v[j] = t[(k16 + j) * 65 + n];
;         const int nn = n0 + n;
;         const int row = mode == 0 ? nn : (256 * (nn >> 7) + (nn & 127) + (mode == 2 ? 128 : 0));
;         u32x4 w0, w1; w0.x = cvt_pk_bf16(v[0], v[1]); w0.y = cvt_pk_bf16(v[2], v[3]); w0.z = cvt_pk_bf16(v[4], v[5]); w0.w = cvt_pk_bf16(v[6], v[7]);
;         w1.x = cvt_pk_bf16(v[8], v[9]); w1.y = cvt_pk_bf16(v[10], v[11]); w1.z = cvt_pk_bf16(v[12], v[13]); w1.w = cvt_pk_bf16(v[14], v[15]);
;         bf16_t* d = dst + (size_t)row * K + k0 + k16;
;         *(u32x4*)d = w0; *(u32x4*)(d + 8) = w1;
;         lds_barrier();
; __device__ __forceinline__ void phase_convert(const Params& p, unsigned char* smem) {
;     ...
;         convT_job(p.in[6] + (size_t)l * 2048 * 5632, (bf16_t*)(p.ws + OFF_IN + (size_t)l * SZ_IN), 2048, 5632, 0, t);
.Lcv_win_lj:
	v_add_u32_e32 v7, s41, v4
	ds_read2st64_b32 v[8:9], v7 offset0:0 offset1:1
	ds_read2st64_b32 v[10:11], v7 offset0:2 offset1:3
	ds_read2st64_b32 v[12:13], v7 offset0:4 offset1:5
	ds_read2st64_b32 v[14:15], v7 offset0:6 offset1:7
	ds_read2st64_b32 v[16:17], v7 offset0:8 offset1:9
	ds_read2st64_b32 v[18:19], v7 offset0:10 offset1:11
	ds_read2st64_b32 v[20:21], v7 offset0:12 offset1:13
	ds_read2st64_b32 v[22:23], v7 offset0:14 offset1:15
	s_mul_hi_u32 s0, s40, 0x2e8ba3
	s_mul_i32 s1, s0, 1408
	s_sub_u32 s1, s40, s1
	s_mul_hi_u32 s2, s1, 0x2e8ba2f
	s_mul_i32 s8, s2, 88
	s_sub_u32 s8, s1, s8
	s_lshl_b32 s9, s8, 6
	s_mul_i32 s9, s9, 0x1000
	s_mul_i32 s28, s0, 0x1600000
	s_add_u32 s9, s9, s28
	s_lshl_b32 s2, s2, 8
	s_add_u32 s9, s9, s2
	s_add_u32 s9, s9, 0x10808000
	s_add_u32 s44, s54, s9
	s_addc_u32 s45, s55, 0
	s_waitcnt lgkmcnt(6)
	v_cvt_pk_bf16_f32 v8, v8, v9
	v_cvt_pk_bf16_f32 v9, v10, v11
	s_waitcnt lgkmcnt(4)
	v_cvt_pk_bf16_f32 v10, v12, v13
	v_cvt_pk_bf16_f32 v11, v14, v15
	s_waitcnt lgkmcnt(2)
	v_cvt_pk_bf16_f32 v12, v16, v17
	v_cvt_pk_bf16_f32 v13, v18, v19
	s_waitcnt lgkmcnt(0)
	v_cvt_pk_bf16_f32 v14, v20, v21
	v_cvt_pk_bf16_f32 v15, v22, v23
	global_store_dwordx4 v5, v[8:11], s[44:45]
	global_store_dwordx4 v5, v[12:15], s[44:45] offset:16
	s_add_u32 s40, s40, s98
	s_add_u32 s41, s41, 0x8000
	s_and_b32 s41, s41, 0x1ffff
	s_cmp_lt_u32 s40, 1408
	s_cbranch_scc1 .Lcv_win_loop
